# NSA compressed branch: compressed key / value fragment loads issued in batches into spare registers instead of load-wait-MFMA one at a time
# speedup vs baseline: 1.0077x; 1.0023x over previous
.LBB0_1288:
	s_and_b64 vcc, exec, s[0:1]
	s_cbranch_vccz .LBB0_1344
	v_bfe_u32 v132, v125, 2, 3
	v_or_b32_e32 v127, s78, v132
	v_lshl_add_u32 v194, s79, 11, v127
	v_mov_b64_e32 v[0:1], s[76:77]
	s_movk_i32 s0, 0x1a00
	v_ashrrev_i32_e32 v133, 5, v125
	v_mad_u64_u32 v[0:1], s[0:1], v194, s0, v[0:1]
	v_and_b32_e32 v41, 3, v125
	s_mov_b64 s[0:1], 0x8200000
	v_lshlrev_b32_e32 v4, 3, v133
	v_lshl_add_u64 v[0:1], v[0:1], 0, s[0:1]
	v_lshlrev_b32_e32 v2, 7, v41
	v_mov_b32_e32 v3, v195
	v_ashrrev_i32_e32 v5, 31, v4
	v_lshl_add_u64 v[2:3], v[0:1], 0, v[2:3]
	v_lshlrev_b64 v[4:5], 1, v[4:5]
	v_lshl_add_u64 v[2:3], v[2:3], 0, v[4:5]
	s_mov_b64 s[0:1], 0x1400
	v_lshl_add_u64 v[6:7], v[2:3], 0, s[0:1]
	v_add_co_u32_e32 v2, vcc, s74, v2
	s_mov_b64 s[0:1], 0x1900
	s_nop 0
	v_addc_co_u32_e32 v3, vcc, 0, v3, vcc
	global_load_dwordx4 v[64:67], v[2:3], off offset:1024
	global_load_dwordx4 v[68:71], v[6:7], off offset:32
	global_load_dwordx4 v[72:75], v[6:7], off offset:64
	global_load_dwordx4 v[76:79], v[6:7], off offset:96
	v_mul_u32_u24_e32 v2, 3, v41
	v_lshlrev_b32_e32 v2, 1, v2
	v_mov_b32_e32 v3, v195
	v_lshl_add_u64 v[0:1], v[0:1], 0, v[2:3]
	v_lshl_add_u64 v[2:3], v[0:1], 0, s[0:1]
	v_add_co_u32_e32 v0, vcc, s74, v0
	s_lshl_b32 s0, s79, 14
	s_nop 0
	v_addc_co_u32_e32 v1, vcc, 0, v1, vcc
	global_load_dword v129, v[0:1], off offset:2304
	global_load_ushort v126, v[2:3], off offset:4
	s_add_u32 s0, s76, s0
	v_and_b32_e32 v128, 31, v125
	v_cmp_lt_u32_e32 vcc, 30, v127
	s_addc_u32 s1, s77, 0
	v_lshlrev_b32_e32 v2, 7, v128
	v_mov_b32_e32 v3, v195
	s_mov_b64 s[4:5], 0x100000
	v_lshlrev_b32_e32 v88, 2, v133
	s_waitcnt vmcnt(1)
	v_cvt_f32_f16_e32 v0, v129
	v_mul_f32_e32 v0, 0xbfb8aa3b, v0
	v_exp_f32_e32 v0, v0
	s_nop 0
	v_add_f32_e32 v20, 1.0, v0
	v_subrev_u32_e32 v0, 31, v127
	v_ashrrev_i32_e32 v0, 4, v0
	v_cndmask_b32_e32 v30, -1, v0, vcc
	v_lshl_add_u64 v[0:1], s[0:1], 0, v[4:5]
	v_lshl_add_u64 v[16:17], v[0:1], 0, v[2:3]
	v_lshl_add_u64 v[26:27], v[16:17], 0, s[4:5]
	s_mov_b32 s4, 0x101000
	v_add_co_u32_e32 v18, vcc, s4, v16
	global_load_dwordx4 v[22:25], v[26:27], off offset:32
	s_nop 0
	v_addc_co_u32_e32 v19, vcc, 0, v17, vcc
	global_load_dwordx4 v[0:3], v[18:19], off offset:-4096
	global_load_dwordx4 v[42:45], v[18:19], off offset:32
	global_load_dwordx4 v[152:155], v[26:27], off offset:64
	global_load_dwordx4 v[156:159], v[26:27], off offset:96
	global_load_dwordx4 v[160:163], v[18:19], off
	global_load_dwordx4 v[164:167], v[18:19], off offset:64
	global_load_dwordx4 v[168:171], v[18:19], off offset:96
	v_cmp_le_i32_e32 vcc, v88, v30
	s_mov_b32 s4, 0xf149f2ca
	v_rcp_f32_e32 v134, v20
	s_waitcnt vmcnt(6)
	v_mfma_f32_32x32x16_f16 v[0:15], v[0:3], v[64:67], 0
	v_mfma_f32_32x32x16_f16 v[0:15], v[22:25], v[68:71], v[0:15]
	s_waitcnt vmcnt(4)
	v_mfma_f32_32x32x16_f16 v[0:15], v[152:155], v[72:75], v[0:15]
	s_waitcnt vmcnt(3)
	v_mfma_f32_32x32x16_f16 v[0:15], v[156:159], v[76:79], v[0:15]
	s_nop 11
	v_cndmask_b32_e32 v37, v193, v0, vcc
	v_cmp_lt_i32_e32 vcc, v88, v30
	s_nop 1
	v_cndmask_b32_e32 v36, v193, v1, vcc
	v_or_b32_e32 v1, 2, v88
	v_cmp_le_i32_e32 vcc, v1, v30
	v_or_b32_e32 v1, 3, v88
	v_max3_f32 v0, v37, s4, v36
	v_cndmask_b32_e32 v35, v193, v2, vcc
	v_cmp_le_i32_e32 vcc, v1, v30
	v_add_u32_e32 v1, 8, v88
	s_mov_b32 s4, 0x102000
	v_cndmask_b32_e32 v34, v193, v3, vcc
	v_cmp_le_i32_e32 vcc, v1, v30
	v_add_u32_e32 v1, 9, v88
	v_max3_f32 v0, v0, v35, v34
	v_cndmask_b32_e32 v33, v193, v4, vcc
	v_cmp_le_i32_e32 vcc, v1, v30
	v_add_u32_e32 v1, 10, v88
	s_nop 0
	v_cndmask_b32_e32 v32, v193, v5, vcc
	v_cmp_le_i32_e32 vcc, v1, v30
	v_add_u32_e32 v1, 11, v88
	v_max3_f32 v0, v0, v33, v32
	v_cndmask_b32_e32 v31, v193, v6, vcc
	v_cmp_le_i32_e32 vcc, v1, v30
	v_add_u32_e32 v1, 16, v88
	s_nop 0
	v_cndmask_b32_e32 v29, v193, v7, vcc
	v_cmp_le_i32_e32 vcc, v1, v30
	v_add_u32_e32 v1, 17, v88
	v_max3_f32 v0, v0, v31, v29
	v_cndmask_b32_e32 v28, v193, v8, vcc
	v_cmp_le_i32_e32 vcc, v1, v30
	v_add_u32_e32 v1, 18, v88
	s_nop 0
	v_cndmask_b32_e32 v27, v193, v9, vcc
	v_cmp_le_i32_e32 vcc, v1, v30
	v_add_u32_e32 v1, 19, v88
	v_max3_f32 v0, v0, v28, v27
	v_cndmask_b32_e32 v26, v193, v10, vcc
	v_cmp_le_i32_e32 vcc, v1, v30
	v_add_u32_e32 v1, 24, v88
	s_nop 0
	v_cndmask_b32_e32 v25, v193, v11, vcc
	v_cmp_le_i32_e32 vcc, v1, v30
	v_add_u32_e32 v1, 25, v88
	v_max3_f32 v0, v0, v26, v25
	v_cndmask_b32_e32 v24, v193, v12, vcc
	v_cmp_le_i32_e32 vcc, v1, v30
	v_add_u32_e32 v1, 26, v88
	s_nop 0
	v_cndmask_b32_e32 v23, v193, v13, vcc
	v_cmp_le_i32_e32 vcc, v1, v30
	v_add_u32_e32 v1, 27, v88
	v_max3_f32 v0, v0, v24, v23
	v_cndmask_b32_e32 v22, v193, v14, vcc
	v_cmp_le_i32_e32 vcc, v1, v30
	s_nop 1
	v_cndmask_b32_e32 v21, v193, v15, vcc
	v_max3_f32 v38, v0, v22, v21
	s_waitcnt vmcnt(2)
	v_mfma_f32_32x32x16_f16 v[0:15], v[160:163], v[64:67], 0
	v_mfma_f32_32x32x16_f16 v[0:15], v[42:45], v[68:71], v[0:15]
	s_waitcnt vmcnt(1)
	v_mfma_f32_32x32x16_f16 v[0:15], v[164:167], v[72:75], v[0:15]
	v_add_u32_e32 v18, 32, v88
	v_cmp_le_i32_e32 vcc, v18, v30
	s_waitcnt vmcnt(0)
	v_mfma_f32_32x32x16_f16 v[0:15], v[168:171], v[76:79], v[0:15]
	s_nop 11
	v_cndmask_b32_e32 v58, v193, v0, vcc
	v_cmp_lt_i32_e32 vcc, v18, v30
	s_nop 1
	v_cndmask_b32_e32 v54, v193, v1, vcc
	v_add_u32_e32 v1, 34, v88
	v_cmp_le_i32_e32 vcc, v1, v30
	v_add_u32_e32 v1, 35, v88
	v_max3_f32 v0, v38, v58, v54
	v_cndmask_b32_e32 v55, v193, v2, vcc
	v_cmp_le_i32_e32 vcc, v1, v30
	v_add_u32_e32 v1, 40, v88
	s_nop 0
	v_cndmask_b32_e32 v56, v193, v3, vcc
	v_cmp_le_i32_e32 vcc, v1, v30
	v_add_u32_e32 v1, 41, v88
	v_max3_f32 v0, v0, v55, v56
	v_cndmask_b32_e32 v57, v193, v4, vcc
	v_cmp_le_i32_e32 vcc, v1, v30
	v_add_u32_e32 v1, 42, v88
	s_nop 0
	v_cndmask_b32_e32 v53, v193, v5, vcc
	v_cmp_le_i32_e32 vcc, v1, v30
	v_add_u32_e32 v1, 43, v88
	v_max3_f32 v0, v0, v57, v53
	v_cndmask_b32_e32 v52, v193, v6, vcc
	v_cmp_le_i32_e32 vcc, v1, v30
	v_add_u32_e32 v1, 48, v88
	s_nop 0
	v_cndmask_b32_e32 v47, v193, v7, vcc
	v_cmp_le_i32_e32 vcc, v1, v30
	v_add_u32_e32 v1, 49, v88
	v_max3_f32 v0, v0, v52, v47
	v_cndmask_b32_e32 v46, v193, v8, vcc
	v_cmp_le_i32_e32 vcc, v1, v30
	v_add_u32_e32 v1, 50, v88
	s_nop 0
	v_cndmask_b32_e32 v45, v193, v9, vcc
	v_cmp_le_i32_e32 vcc, v1, v30
	v_add_u32_e32 v1, 51, v88
	v_max3_f32 v0, v0, v46, v45
	v_cndmask_b32_e32 v44, v193, v10, vcc
	v_cmp_le_i32_e32 vcc, v1, v30
	v_add_u32_e32 v1, 56, v88
	s_nop 0
	v_cndmask_b32_e32 v43, v193, v11, vcc
	v_cmp_le_i32_e32 vcc, v1, v30
	v_add_u32_e32 v1, 57, v88
	v_max3_f32 v0, v0, v44, v43
	v_cndmask_b32_e32 v42, v193, v12, vcc
	v_cmp_le_i32_e32 vcc, v1, v30
	v_add_u32_e32 v1, 58, v88
	s_nop 0
	v_cndmask_b32_e32 v40, v193, v13, vcc
	v_cmp_le_i32_e32 vcc, v1, v30
	v_add_u32_e32 v1, 59, v88
	v_max3_f32 v0, v0, v42, v40
	v_cndmask_b32_e32 v39, v193, v14, vcc
	v_cmp_le_i32_e32 vcc, v1, v30
	s_nop 1
	v_cndmask_b32_e32 v38, v193, v15, vcc
	v_add_co_u32_e32 v18, vcc, s4, v16
	s_mov_b32 s4, 0x103000
	s_nop 0
	v_addc_co_u32_e32 v19, vcc, 0, v17, vcc
	v_add_co_u32_e32 v16, vcc, s4, v16
	v_max3_f32 v59, v0, v39, v38
	s_nop 0
	v_addc_co_u32_e32 v17, vcc, 0, v17, vcc
	global_load_dwordx4 v[0:3], v[16:17], off offset:-4096
	global_load_dwordx4 v[98:101], v[16:17], off offset:32
	global_load_dwordx4 v[48:51], v[18:19], off offset:32
	global_load_dwordx4 v[172:175], v[18:19], off offset:64
	global_load_dwordx4 v[176:179], v[18:19], off offset:96
	global_load_dwordx4 v[180:183], v[16:17], off
	global_load_dwordx4 v[184:187], v[16:17], off offset:64
	global_load_dwordx4 v[188:191], v[16:17], off offset:96
	s_waitcnt vmcnt(7)
	v_mfma_f32_32x32x16_f16 v[0:15], v[0:3], v[64:67], 0
	v_readlane_b32 s4, v252, 31
	s_nop 1
	v_lshl_add_u32 v130, v125, 2, s4
	s_waitcnt vmcnt(5)
	v_mfma_f32_32x32x16_f16 v[0:15], v[48:51], v[68:71], v[0:15]
	s_waitcnt vmcnt(4)
	v_mfma_f32_32x32x16_f16 v[0:15], v[172:175], v[72:75], v[0:15]
	v_add_u32_e32 v18, 64, v88
	v_cmp_le_i32_e32 vcc, v18, v30
	s_waitcnt vmcnt(3)
	v_mfma_f32_32x32x16_f16 v[0:15], v[176:179], v[76:79], v[0:15]
	s_nop 11
	v_cndmask_b32_e32 v97, v193, v0, vcc
	v_cmp_lt_i32_e32 vcc, v18, v30
	s_nop 1
	v_cndmask_b32_e32 v96, v193, v1, vcc
	v_add_u32_e32 v1, 0x42, v88
	v_cmp_le_i32_e32 vcc, v1, v30
	v_add_u32_e32 v1, 0x43, v88
	v_max3_f32 v0, v59, v97, v96
	v_cndmask_b32_e32 v59, v193, v2, vcc
	v_cmp_le_i32_e32 vcc, v1, v30
	v_add_u32_e32 v1, 0x48, v88
	s_nop 0
	v_cndmask_b32_e32 v60, v193, v3, vcc
	v_cmp_le_i32_e32 vcc, v1, v30
	v_add_u32_e32 v1, 0x49, v88
	v_max3_f32 v0, v0, v59, v60
	v_cndmask_b32_e32 v61, v193, v4, vcc
	v_cmp_le_i32_e32 vcc, v1, v30
	v_add_u32_e32 v1, 0x4a, v88
	s_nop 0
	v_cndmask_b32_e32 v80, v193, v5, vcc
	v_cmp_le_i32_e32 vcc, v1, v30
	v_add_u32_e32 v1, 0x4b, v88
	v_max3_f32 v0, v0, v61, v80
	v_cndmask_b32_e32 v81, v193, v6, vcc
	v_cmp_le_i32_e32 vcc, v1, v30
	v_add_u32_e32 v1, 0x50, v88
	s_nop 0
	v_cndmask_b32_e32 v95, v193, v7, vcc
	v_cmp_le_i32_e32 vcc, v1, v30
	v_add_u32_e32 v1, 0x51, v88
	v_max3_f32 v0, v0, v81, v95
	v_cndmask_b32_e32 v94, v193, v8, vcc
	v_cmp_le_i32_e32 vcc, v1, v30
	v_add_u32_e32 v1, 0x52, v88
	s_nop 0
	v_cndmask_b32_e32 v84, v193, v9, vcc
	v_cmp_le_i32_e32 vcc, v1, v30
	v_add_u32_e32 v1, 0x53, v88
	v_max3_f32 v0, v0, v94, v84
	v_cndmask_b32_e32 v85, v193, v10, vcc
	v_cmp_le_i32_e32 vcc, v1, v30
	v_add_u32_e32 v1, 0x58, v88
	s_nop 0
	v_cndmask_b32_e32 v92, v193, v11, vcc
	v_cmp_le_i32_e32 vcc, v1, v30
	v_add_u32_e32 v1, 0x59, v88
	v_max3_f32 v0, v0, v85, v92
	v_cndmask_b32_e32 v93, v193, v12, vcc
	v_cmp_le_i32_e32 vcc, v1, v30
	v_add_u32_e32 v1, 0x5a, v88
	s_nop 0
	v_cndmask_b32_e32 v89, v193, v13, vcc
	v_cmp_le_i32_e32 vcc, v1, v30
	v_add_u32_e32 v1, 0x5b, v88
	v_max3_f32 v0, v0, v93, v89
	v_cndmask_b32_e32 v87, v193, v14, vcc
	v_cmp_le_i32_e32 vcc, v1, v30
	s_nop 1
	v_cndmask_b32_e32 v86, v193, v15, vcc
	v_max3_f32 v48, v0, v87, v86
	s_waitcnt vmcnt(2)
	v_mfma_f32_32x32x16_f16 v[0:15], v[180:183], v[64:67], 0
	v_mfma_f32_32x32x16_f16 v[0:15], v[98:101], v[68:71], v[0:15]
	s_waitcnt vmcnt(1)
	v_mfma_f32_32x32x16_f16 v[0:15], v[184:187], v[72:75], v[0:15]
	s_waitcnt vmcnt(0)
	v_mfma_f32_32x32x16_f16 v[0:15], v[188:191], v[76:79], v[0:15]
	v_add_u32_e32 v16, 0x60, v88
	v_cmp_le_i32_e32 vcc, v16, v30
	s_nop 9
	v_cndmask_b32_e32 v17, v193, v0, vcc
	v_cmp_lt_i32_e32 vcc, v16, v30
	s_nop 1
	v_cndmask_b32_e32 v16, v193, v1, vcc
	v_add_u32_e32 v1, 0x62, v88
	v_cmp_le_i32_e32 vcc, v1, v30
	v_add_u32_e32 v1, 0x63, v88
	v_max3_f32 v0, v48, v17, v16
	v_cndmask_b32_e32 v18, v193, v2, vcc
	v_cmp_le_i32_e32 vcc, v1, v30
	v_add_u32_e32 v1, 0x68, v88
	s_nop 0
	v_cndmask_b32_e32 v19, v193, v3, vcc
	v_cmp_le_i32_e32 vcc, v1, v30
	v_add_u32_e32 v1, 0x69, v88
	v_max3_f32 v0, v0, v18, v19
	v_cndmask_b32_e32 v98, v193, v4, vcc
	v_cmp_le_i32_e32 vcc, v1, v30
	v_add_u32_e32 v1, 0x6a, v88
	s_nop 0
	v_cndmask_b32_e32 v99, v193, v5, vcc
	v_cmp_le_i32_e32 vcc, v1, v30
	v_add_u32_e32 v1, 0x6b, v88
	v_max3_f32 v0, v0, v98, v99
	v_cndmask_b32_e32 v6, v193, v6, vcc
	v_cmp_le_i32_e32 vcc, v1, v30
	v_add_u32_e32 v1, 0x70, v88
	s_nop 0
	v_cndmask_b32_e32 v7, v193, v7, vcc
	v_cmp_le_i32_e32 vcc, v1, v30
	v_add_u32_e32 v1, 0x71, v88
	v_max3_f32 v0, v0, v6, v7
	v_cndmask_b32_e32 v8, v193, v8, vcc
	v_cmp_le_i32_e32 vcc, v1, v30
	v_add_u32_e32 v1, 0x72, v88
	s_nop 0
	v_cndmask_b32_e32 v9, v193, v9, vcc
	v_cmp_le_i32_e32 vcc, v1, v30
	v_add_u32_e32 v1, 0x73, v88
	v_max3_f32 v0, v0, v8, v9
	v_cndmask_b32_e32 v10, v193, v10, vcc
	v_cmp_le_i32_e32 vcc, v1, v30
	v_add_u32_e32 v1, 0x78, v88
	s_nop 0
	v_cndmask_b32_e32 v11, v193, v11, vcc
	v_cmp_le_i32_e32 vcc, v1, v30
	v_add_u32_e32 v1, 0x79, v88
	v_max3_f32 v0, v0, v10, v11
	v_cndmask_b32_e32 v12, v193, v12, vcc
	v_cmp_le_i32_e32 vcc, v1, v30
	v_add_u32_e32 v1, 0x7a, v88
	s_nop 0
	v_cndmask_b32_e32 v13, v193, v13, vcc
	v_cmp_le_i32_e32 vcc, v1, v30
	v_add_u32_e32 v1, 0x7b, v88
	v_max3_f32 v0, v0, v12, v13
	v_cndmask_b32_e32 v14, v193, v14, vcc
	v_cmp_le_i32_e32 vcc, v1, v30
	v_mov_b32_e32 v1, v192
	s_nop 0
	v_cndmask_b32_e32 v15, v193, v15, vcc
	v_lshlrev_b32_e32 v1, 2, v1
	v_max3_f32 v0, v0, v14, v15
	v_xor_b32_e32 v1, 0x80, v1
	ds_bpermute_b32 v1, v1, v0
	s_waitcnt lgkmcnt(0)
	v_max_f32_e32 v1, v1, v1
	v_max_f32_e32 v20, v0, v1
	v_sub_f32_e32 v0, v37, v20
	v_exp_f32_e32 v135, v0
	v_sub_f32_e32 v0, v36, v20
	v_exp_f32_e32 v0, v0
	v_sub_f32_e32 v29, v29, v20
	v_add_f32_e32 v1, 0, v135
	v_exp_f32_e32 v137, v29
	v_add_f32_e32 v2, v0, v1
	v_sub_f32_e32 v1, v35, v20
	v_exp_f32_e32 v1, v1
	v_sub_f32_e32 v28, v28, v20
	v_exp_f32_e32 v136, v28
	v_sub_f32_e32 v27, v27, v20
	v_add_f32_e32 v3, v1, v2
	v_sub_f32_e32 v2, v34, v20
	v_exp_f32_e32 v2, v2
	v_exp_f32_e32 v48, v27
	v_sub_f32_e32 v26, v26, v20
	v_exp_f32_e32 v49, v26
	v_add_f32_e32 v4, v2, v3
	v_sub_f32_e32 v3, v33, v20
	v_exp_f32_e32 v3, v3
	v_sub_f32_e32 v25, v25, v20
	v_exp_f32_e32 v50, v25
	v_sub_f32_e32 v24, v24, v20
	v_add_f32_e32 v5, v3, v4
	v_sub_f32_e32 v4, v32, v20
	v_exp_f32_e32 v4, v4
	v_exp_f32_e32 v51, v24
	v_sub_f32_e32 v23, v23, v20
	v_exp_f32_e32 v62, v23
	v_add_f32_e32 v30, v4, v5
	v_sub_f32_e32 v5, v31, v20
	v_exp_f32_e32 v5, v5
	v_sub_f32_e32 v22, v22, v20
	v_exp_f32_e32 v63, v22
	v_sub_f32_e32 v21, v21, v20
	v_add_f32_e32 v30, v5, v30
	v_add_f32_e32 v29, v137, v30
	v_add_f32_e32 v28, v136, v29
	v_add_f32_e32 v27, v48, v28
	v_add_f32_e32 v26, v49, v27
	v_add_f32_e32 v25, v50, v26
	v_exp_f32_e32 v139, v21
	v_add_f32_e32 v24, v51, v25
	v_add_f32_e32 v23, v62, v24
	v_add_f32_e32 v22, v63, v23
	v_add_f32_e32 v21, v139, v22
	v_sub_f32_e32 v22, v58, v20
	v_exp_f32_e32 v138, v22
	v_sub_f32_e32 v22, v54, v20
	v_exp_f32_e32 v54, v22
	v_sub_f32_e32 v22, v55, v20
	v_exp_f32_e32 v55, v22
	v_sub_f32_e32 v22, v56, v20
	v_exp_f32_e32 v56, v22
	v_sub_f32_e32 v22, v57, v20
	v_add_f32_e32 v21, v138, v21
	v_exp_f32_e32 v57, v22
	v_sub_f32_e32 v22, v53, v20
	v_add_f32_e32 v21, v54, v21
	v_exp_f32_e32 v82, v22
	v_sub_f32_e32 v22, v52, v20
	v_add_f32_e32 v21, v55, v21
	v_exp_f32_e32 v83, v22
	v_sub_f32_e32 v22, v47, v20
	v_add_f32_e32 v21, v56, v21
	v_exp_f32_e32 v141, v22
	v_sub_f32_e32 v22, v46, v20
	v_add_f32_e32 v21, v57, v21
	v_exp_f32_e32 v140, v22
	v_sub_f32_e32 v22, v45, v20
	v_add_f32_e32 v21, v82, v21
	v_exp_f32_e32 v32, v22
	v_sub_f32_e32 v22, v44, v20
	v_add_f32_e32 v21, v83, v21
	v_exp_f32_e32 v33, v22
	v_sub_f32_e32 v22, v43, v20
	v_add_f32_e32 v21, v141, v21
	v_exp_f32_e32 v34, v22
	v_sub_f32_e32 v22, v42, v20
	v_add_f32_e32 v21, v140, v21
	v_exp_f32_e32 v35, v22
	v_sub_f32_e32 v22, v40, v20
	v_add_f32_e32 v21, v32, v21
	v_exp_f32_e32 v36, v22
	v_sub_f32_e32 v22, v39, v20
	v_add_f32_e32 v21, v33, v21
	v_exp_f32_e32 v37, v22
	v_sub_f32_e32 v22, v38, v20
	v_add_f32_e32 v21, v34, v21
	v_exp_f32_e32 v143, v22
	v_sub_f32_e32 v22, v97, v20
	v_add_f32_e32 v21, v35, v21
	v_exp_f32_e32 v142, v22
	v_sub_f32_e32 v22, v96, v20
	v_add_f32_e32 v21, v36, v21
	v_exp_f32_e32 v58, v22
	v_sub_f32_e32 v22, v59, v20
	v_add_f32_e32 v21, v37, v21
	v_exp_f32_e32 v59, v22
	v_sub_f32_e32 v22, v60, v20
	v_add_f32_e32 v21, v143, v21
	v_exp_f32_e32 v60, v22
	v_sub_f32_e32 v22, v61, v20
	v_add_f32_e32 v21, v142, v21
	v_exp_f32_e32 v61, v22
	v_sub_f32_e32 v22, v80, v20
	v_add_f32_e32 v21, v58, v21
	v_exp_f32_e32 v80, v22
	v_sub_f32_e32 v22, v81, v20
	v_add_f32_e32 v21, v59, v21
	v_exp_f32_e32 v81, v22
	v_sub_f32_e32 v22, v95, v20
	v_add_f32_e32 v21, v60, v21
	v_exp_f32_e32 v145, v22
	v_sub_f32_e32 v22, v94, v20
	v_add_f32_e32 v21, v61, v21
	v_exp_f32_e32 v144, v22
	v_sub_f32_e32 v22, v84, v20
	v_add_f32_e32 v21, v80, v21
	v_exp_f32_e32 v84, v22
	v_sub_f32_e32 v22, v85, v20
	v_add_f32_e32 v21, v81, v21
	v_exp_f32_e32 v85, v22
	v_sub_f32_e32 v22, v92, v20
	v_add_f32_e32 v21, v145, v21
	v_exp_f32_e32 v92, v22
	v_sub_f32_e32 v22, v93, v20
	v_add_f32_e32 v21, v144, v21
	v_exp_f32_e32 v93, v22
	v_sub_f32_e32 v22, v89, v20
	v_add_f32_e32 v21, v84, v21
	v_exp_f32_e32 v96, v22
	v_sub_f32_e32 v22, v87, v20
	v_add_f32_e32 v21, v85, v21
	v_exp_f32_e32 v97, v22
	v_sub_f32_e32 v22, v86, v20
	v_add_f32_e32 v21, v92, v21
	v_exp_f32_e32 v150, v22
	v_sub_f32_e32 v17, v17, v20
	v_add_f32_e32 v21, v93, v21
	v_exp_f32_e32 v148, v17
	v_sub_f32_e32 v16, v16, v20
	v_add_f32_e32 v21, v96, v21
	v_exp_f32_e32 v112, v16
	v_add_f32_e32 v21, v97, v21
	v_add_f32_e32 v21, v150, v21
	v_add_f32_e32 v17, v148, v21
	v_add_f32_e32 v16, v112, v17
	v_sub_f32_e32 v17, v18, v20
	v_exp_f32_e32 v113, v17
	v_sub_f32_e32 v17, v19, v20
	v_exp_f32_e32 v114, v17
	v_sub_f32_e32 v17, v98, v20
	v_exp_f32_e32 v115, v17
	v_sub_f32_e32 v17, v99, v20
	v_exp_f32_e32 v118, v17
	v_sub_f32_e32 v6, v6, v20
	v_add_f32_e32 v16, v113, v16
	v_exp_f32_e32 v119, v6
	v_sub_f32_e32 v7, v7, v20
	v_add_f32_e32 v16, v114, v16
	v_exp_f32_e32 v149, v7
	v_sub_f32_e32 v7, v8, v20
	v_add_f32_e32 v16, v115, v16
	v_exp_f32_e32 v146, v7
	v_sub_f32_e32 v7, v9, v20
	v_add_f32_e32 v16, v118, v16
	v_exp_f32_e32 v116, v7
	v_sub_f32_e32 v7, v10, v20
	v_add_f32_e32 v6, v119, v16
	v_exp_f32_e32 v117, v7
	v_sub_f32_e32 v7, v11, v20
	v_add_f32_e32 v6, v149, v6
	v_exp_f32_e32 v120, v7
	v_sub_f32_e32 v7, v12, v20
	v_add_f32_e32 v6, v146, v6
	v_exp_f32_e32 v121, v7
	v_sub_f32_e32 v7, v13, v20
	v_add_f32_e32 v6, v116, v6
	v_exp_f32_e32 v122, v7
	v_sub_f32_e32 v7, v14, v20
	v_add_f32_e32 v6, v117, v6
	v_exp_f32_e32 v123, v7
	v_sub_f32_e32 v7, v15, v20
	v_add_f32_e32 v6, v120, v6
	v_exp_f32_e32 v147, v7
	v_add_f32_e32 v6, v121, v6
	v_mov_b32_e32 v7, v192
	v_add_f32_e32 v6, v122, v6
	v_add_f32_e32 v6, v123, v6
	v_lshlrev_b32_e32 v7, 2, v7
	v_add_f32_e32 v6, v147, v6
	v_xor_b32_e32 v7, 0x80, v7
	ds_bpermute_b32 v7, v7, v6
	v_ashrrev_i32_e32 v89, 31, v88
	s_waitcnt lgkmcnt(0)
	v_add_f32_e32 v6, v6, v7
	v_cmp_lt_f32_e32 vcc, 0, v6
	v_rcp_f32_e32 v6, v6
	v_mov_b32_e32 v7, v195
	v_cndmask_b32_e32 v40, 0, v6, vcc
	v_lshlrev_b32_e32 v6, 8, v128
	v_lshl_add_u64 v[6:7], s[0:1], 0, v[6:7]
	v_lshl_add_u64 v[8:9], v[88:89], 1, v[6:7]
	s_mov_b64 s[0:1], 0x120000
	v_lshl_add_u64 v[38:39], v[8:9], 0, s[0:1]
	s_mov_b32 s0, 0x120000
	v_pk_mul_f32 v[44:45], v[4:5], v[40:41] op_sel_hi:[1,0]
	v_add_co_u32_e32 v4, vcc, s0, v8
	s_mov_b32 s0, 0x122000
	s_nop 0
	v_addc_co_u32_e32 v5, vcc, 0, v9, vcc
	v_pk_mul_f32 v[46:47], v[0:1], v[40:41] op_sel_hi:[1,0]
	v_add_co_u32_e32 v86, vcc, s0, v8
	v_fma_mixlo_f16 v6, v135, v40, 0
	v_cvt_pk_f16_f32 v1, v46, v47
	v_addc_co_u32_e32 v87, vcc, 0, v9, vcc
	v_pack_b32_f16 v0, v6, v1
	global_load_dwordx2 v[4:5], v[4:5], off
	s_nop 0
	global_load_dwordx2 v[6:7], v[38:39], off offset:16
	global_load_dwordx2 v[8:9], v[86:87], off
	global_load_dwordx2 v[10:11], v[86:87], off offset:16
	global_load_dwordx2 v[102:103], v[38:39], off offset:32
	global_load_dwordx2 v[104:105], v[38:39], off offset:48
	global_load_dwordx2 v[106:107], v[86:87], off offset:32
	global_load_dwordx2 v[108:109], v[86:87], off offset:48
	global_load_dwordx2 v[152:153], v[38:39], off offset:64
	global_load_dwordx2 v[154:155], v[38:39], off offset:80
	global_load_dwordx2 v[156:157], v[86:87], off offset:64
	global_load_dwordx2 v[158:159], v[86:87], off offset:80
	global_load_dwordx2 v[160:161], v[38:39], off offset:96
	global_load_dwordx2 v[162:163], v[38:39], off offset:112
	global_load_dwordx2 v[164:165], v[86:87], off offset:96
	global_load_dwordx2 v[166:167], v[86:87], off offset:112
	global_load_dwordx2 v[168:169], v[38:39], off offset:128
	global_load_dwordx2 v[170:171], v[38:39], off offset:144
	global_load_dwordx2 v[172:173], v[86:87], off offset:128
	global_load_dwordx2 v[174:175], v[86:87], off offset:144
	global_load_dwordx2 v[176:177], v[38:39], off offset:160
	global_load_dwordx2 v[178:179], v[38:39], off offset:176
	global_load_dwordx2 v[180:181], v[86:87], off offset:160
	global_load_dwordx2 v[182:183], v[86:87], off offset:176
	global_load_dwordx2 v[184:185], v[38:39], off offset:192
	global_load_dwordx2 v[186:187], v[38:39], off offset:208
	global_load_dwordx2 v[188:189], v[86:87], off offset:192
	global_load_dwordx2 v[190:191], v[86:87], off offset:208
	v_pk_mul_f32 v[42:43], v[2:3], v[40:41] op_sel_hi:[1,0]
	v_cvt_pk_f16_f32 v3, v44, v45
	v_cvt_pk_f16_f32 v2, v42, v43
	v_alignbit_b32 v1, v2, v1, 16
	v_alignbit_b32 v2, v3, v2, 16
	v_lshrrev_b32_e32 v3, 16, v3
	v_fma_mixhi_f16 v3, v137, v40, 0
	v_pk_mul_f32 v[52:53], v[48:49], v[40:41] op_sel_hi:[1,0]
	v_pk_mul_f32 v[48:49], v[50:51], v[40:41] op_sel_hi:[1,0]
	s_waitcnt vmcnt(26)
	v_mfma_f32_32x32x16_f16 v[16:31], v[4:7], v[0:3], 0
	v_mul_f32_e64 v50, v62, v40
	v_mul_f32_e64 v51, v63, v40
	v_fma_mixlo_f16 v94, v136, v40, 0
	v_cvt_pk_f16_f32 v95, v52, v53
	v_cvt_pk_f16_f32 v62, v50, v51
	v_pack_b32_f16 v98, v94, v95
	v_cvt_pk_f16_f32 v94, v48, v49
	v_lshrrev_b32_e32 v101, 16, v62
	s_waitcnt vmcnt(24)
	v_mfma_f32_32x32x16_f16 v[0:15], v[8:11], v[0:3], 0
	v_alignbit_b32 v99, v94, v95, 16
	v_alignbit_b32 v100, v62, v94, 16
	v_fma_mixhi_f16 v101, v139, v40, 0
	v_mul_f32_e64 v62, v54, v40
	v_mul_f32_e64 v63, v55, v40
	v_pk_mul_f32 v[54:55], v[56:57], v[40:41] op_sel_hi:[1,0]
	v_pk_mul_f32 v[56:57], v[82:83], v[40:41] op_sel_hi:[1,0]
	v_fma_mixlo_f16 v94, v138, v40, 0
	s_waitcnt vmcnt(22)
	v_mfma_f32_32x32x16_f16 v[16:31], v[102:105], v[98:101], v[16:31]
	v_cvt_pk_f16_f32 v95, v62, v63
	v_cvt_pk_f16_f32 v82, v56, v57
	v_mul_f32_e64 v110, v32, v40
	v_mul_f32_e64 v111, v33, v40
	v_mul_f32_e64 v96, v96, v40
	v_mul_f32_e64 v97, v97, v40
	v_cvt_pk_f16_f32 v33, v110, v111
	v_fmac_f32_e32 v46, v135, v40
	v_cmp_eq_u32_e32 vcc, 0, v41
	s_waitcnt vmcnt(20)
	v_mfma_f32_32x32x16_f16 v[0:15], v[106:109], v[98:101], v[0:15]
	v_pack_b32_f16 v98, v94, v95
	v_cvt_pk_f16_f32 v94, v54, v55
	v_lshrrev_b32_e32 v101, 16, v82
	v_alignbit_b32 v99, v94, v95, 16
	v_alignbit_b32 v100, v82, v94, 16
	v_fma_mixhi_f16 v101, v141, v40, 0
	v_fma_mixlo_f16 v82, v140, v40, 0
	v_pack_b32_f16 v32, v82, v33
	s_waitcnt vmcnt(18)
	v_mfma_f32_32x32x16_f16 v[16:31], v[152:155], v[98:101], v[16:31]
	v_mul_f32_e64 v94, v92, v40
	v_mul_f32_e64 v95, v93, v40
	v_mul_f32_e64 v92, v112, v40
	v_mul_f32_e64 v93, v113, v40
	s_waitcnt vmcnt(16)
	v_mfma_f32_32x32x16_f16 v[0:15], v[156:159], v[98:101], v[0:15]
	v_mul_f32_e64 v106, v34, v40
	v_mul_f32_e64 v107, v35, v40
	v_pk_mul_f32 v[108:109], v[36:37], v[40:41] op_sel_hi:[1,0]
	v_cvt_pk_f16_f32 v34, v106, v107
	v_cvt_pk_f16_f32 v35, v108, v109
	v_alignbit_b32 v33, v34, v33, 16
	v_alignbit_b32 v34, v35, v34, 16
	v_lshrrev_b32_e32 v35, 16, v35
	v_fma_mixhi_f16 v35, v143, v40, 0
	s_waitcnt vmcnt(14)
	s_nop 0
	v_mfma_f32_32x32x16_f16 v[16:31], v[160:163], v[32:35], v[16:31]
	v_mul_f32_e64 v100, v60, v40
	v_mul_f32_e64 v101, v61, v40
	v_mul_f32_e64 v98, v84, v40
	v_mul_f32_e64 v99, v85, v40
	v_mul_f32_e64 v84, v118, v40
	v_mul_f32_e64 v85, v119, v40
	s_waitcnt vmcnt(12)
	v_mfma_f32_32x32x16_f16 v[0:15], v[164:167], v[32:35], v[0:15]
	v_mul_f32_e64 v104, v58, v40
	v_mul_f32_e64 v105, v59, v40
	v_mul_f32_e64 v102, v80, v40
	v_mul_f32_e64 v103, v81, v40
	v_fma_mixlo_f16 v32, v142, v40, 0
	v_cvt_pk_f16_f32 v33, v104, v105
	v_cvt_pk_f16_f32 v34, v100, v101
	v_cvt_pk_f16_f32 v35, v102, v103
	v_pack_b32_f16 v32, v32, v33
	v_alignbit_b32 v33, v34, v33, 16
	v_alignbit_b32 v34, v35, v34, 16
	v_lshrrev_b32_e32 v35, 16, v35
	v_fma_mixhi_f16 v35, v145, v40, 0
	s_waitcnt vmcnt(10)
	s_nop 0
	v_mfma_f32_32x32x16_f16 v[16:31], v[168:171], v[32:35], v[16:31]
	s_waitcnt vmcnt(8)
	v_mfma_f32_32x32x16_f16 v[0:15], v[172:175], v[32:35], v[0:15]
	v_fma_mixlo_f16 v32, v144, v40, 0
	v_cvt_pk_f16_f32 v33, v98, v99
	v_cvt_pk_f16_f32 v34, v94, v95
	v_cvt_pk_f16_f32 v35, v96, v97
	v_pack_b32_f16 v32, v32, v33
	v_alignbit_b32 v33, v34, v33, 16
	v_alignbit_b32 v34, v35, v34, 16
	v_lshrrev_b32_e32 v35, 16, v35
	v_fma_mixhi_f16 v35, v150, v40, 0
	s_waitcnt vmcnt(6)
	s_nop 0
	v_mfma_f32_32x32x16_f16 v[16:31], v[176:179], v[32:35], v[16:31]
	s_waitcnt vmcnt(4)
	v_mfma_f32_32x32x16_f16 v[0:15], v[180:183], v[32:35], v[0:15]
	v_mul_f32_e64 v82, v114, v40
	v_mul_f32_e64 v83, v115, v40
	v_fma_mixlo_f16 v32, v148, v40, 0
	v_cvt_pk_f16_f32 v33, v92, v93
	v_cvt_pk_f16_f32 v34, v82, v83
	v_cvt_pk_f16_f32 v35, v84, v85
	v_pack_b32_f16 v32, v32, v33
	v_alignbit_b32 v33, v34, v33, 16
	v_alignbit_b32 v34, v35, v34, 16
	v_lshrrev_b32_e32 v35, 16, v35
	v_fma_mixhi_f16 v35, v149, v40, 0
	v_pk_mul_f32 v[80:81], v[116:117], v[40:41] op_sel_hi:[1,0]
	s_waitcnt vmcnt(0)
	v_mfma_f32_32x32x16_f16 v[0:15], v[188:191], v[32:35], v[0:15]
	global_load_dwordx2 v[36:37], v[38:39], off offset:224
	s_nop 0
	global_load_dwordx2 v[38:39], v[38:39], off offset:240
	s_nop 0
	global_load_dwordx2 v[112:113], v[86:87], off offset:224
	global_load_dwordx2 v[114:115], v[86:87], off offset:240
	v_mfma_f32_32x32x16_f16 v[16:31], v[184:187], v[32:35], v[16:31]
	v_mul_f32_e64 v58, v120, v40
	v_mul_f32_e64 v59, v121, v40
	v_mul_f32_e64 v60, v122, v40
	v_mul_f32_e64 v61, v123, v40
	v_fma_mixlo_f16 v32, v146, v40, 0
	v_cvt_pk_f16_f32 v33, v80, v81
	v_cvt_pk_f16_f32 v34, v58, v59
	v_cvt_pk_f16_f32 v35, v60, v61
	v_pack_b32_f16 v32, v32, v33
	v_alignbit_b32 v33, v34, v33, 16
	v_alignbit_b32 v34, v35, v34, 16
	v_lshrrev_b32_e32 v35, 16, v35
	v_fma_mixhi_f16 v35, v147, v40, 0
	s_waitcnt vmcnt(0)
	s_nop 0
	v_mfma_f32_32x32x16_f16 v[0:15], v[112:115], v[32:35], v[0:15]
	s_nop 11
	v_mul_f32_e32 v0, v134, v0
	v_mfma_f32_32x32x16_f16 v[16:31], v[36:39], v[32:35], v[16:31]
	v_mul_f32_e32 v1, v134, v1
	ds_write2st64_b32 v130, v0, v1 offset0:16 offset1:17
	v_mul_f32_e32 v1, v134, v2
	s_nop 8
	v_mul_f32_e32 v0, v134, v18
	v_mul_f32_e32 v2, v134, v19
	ds_write2st64_b32 v130, v0, v2 offset0:2 offset1:3
	v_mul_f32_e32 v0, v134, v3
	ds_write2st64_b32 v130, v1, v0 offset0:18 offset1:19
	v_mul_f32_e32 v0, v134, v20
	v_mul_f32_e32 v2, v134, v21
	v_mul_f32_e32 v1, v134, v4
	ds_write2st64_b32 v130, v0, v2 offset0:4 offset1:5
	v_mul_f32_e32 v0, v134, v5
	ds_write2st64_b32 v130, v1, v0 offset0:20 offset1:21
	v_mul_f32_e32 v0, v134, v22
	v_mul_f32_e32 v2, v134, v23
	v_mul_f32_e32 v1, v134, v6
	ds_write2st64_b32 v130, v0, v2 offset0:6 offset1:7
	v_mul_f32_e32 v0, v134, v7
	ds_write2st64_b32 v130, v1, v0 offset0:22 offset1:23
	v_mul_f32_e32 v0, v134, v24
	v_mul_f32_e32 v2, v134, v25
	v_mul_f32_e32 v1, v134, v8
	ds_write2st64_b32 v130, v0, v2 offset0:8 offset1:9
	v_mul_f32_e32 v0, v134, v9
	ds_write2st64_b32 v130, v1, v0 offset0:24 offset1:25
	v_mul_f32_e32 v0, v134, v26
	v_mul_f32_e32 v2, v134, v27
	v_mul_f32_e32 v1, v134, v10
	ds_write2st64_b32 v130, v0, v2 offset0:10 offset1:11
	v_mul_f32_e32 v0, v134, v11
	ds_write2st64_b32 v130, v1, v0 offset0:26 offset1:27
	v_mul_f32_e32 v0, v134, v28
	v_mul_f32_e32 v2, v134, v29
	v_mul_f32_e32 v1, v134, v12
	ds_write2st64_b32 v130, v0, v2 offset0:12 offset1:13
	v_mul_f32_e32 v0, v134, v13
	ds_write2st64_b32 v130, v1, v0 offset0:28 offset1:29
	v_mul_f32_e32 v0, v134, v30
	v_mul_f32_e32 v2, v134, v31
	v_mul_f32_e32 v1, v134, v14
	ds_write2st64_b32 v130, v0, v2 offset0:14 offset1:15
	v_mul_f32_e32 v0, v134, v15
	ds_write2st64_b32 v130, v1, v0 offset0:30 offset1:31
	v_add_f32_e32 v1, v47, v42
	v_add_f32_e32 v1, v46, v1
	v_lshl_add_u32 v0, v132, 5, v133
	v_add_f32_dpp v3, v42, v42 quad_perm:[1,0,3,2] row_mask:0xf bank_mask:0xf bound_ctrl:1
	v_add_f32_dpp v1, v1, v1 quad_perm:[1,0,3,2] row_mask:0xf bank_mask:0xf bound_ctrl:1
	v_mul_f32_e32 v16, v134, v16
	v_mul_f32_e32 v17, v134, v17
	v_mov_b32_dpp v2, v1 quad_perm:[2,3,0,1] row_mask:0xf bank_mask:0xf bound_ctrl:1
	v_mov_b32_dpp v4, v3 quad_perm:[2,3,0,1] row_mask:0xf bank_mask:0xf bound_ctrl:1
	v_lshl_add_u32 v0, v0, 2, s89
	ds_write2st64_b32 v130, v16, v17 offset1:1
	s_and_saveexec_b64 s[0:1], vcc
	v_add_f32_e32 v1, v1, v2
	v_add_f32_e32 v2, v3, v4
	ds_write2st64_b32 v0, v1, v2 offset1:4
	s_or_b64 exec, exec, s[0:1]
	v_mul_f32_e32 v3, v137, v40
	v_add_f32_e32 v1, v43, v44
	v_add_f32_e32 v2, v45, v3
	v_add_f32_e32 v1, v1, v2
	v_add_f32_dpp v3, v3, v3 quad_perm:[1,0,3,2] row_mask:0xf bank_mask:0xf bound_ctrl:1
	s_nop 0
	v_add_f32_dpp v1, v1, v1 quad_perm:[1,0,3,2] row_mask:0xf bank_mask:0xf bound_ctrl:1
	v_mov_b32_dpp v4, v3 quad_perm:[2,3,0,1] row_mask:0xf bank_mask:0xf bound_ctrl:1
	s_nop 0
	v_mov_b32_dpp v2, v1 quad_perm:[2,3,0,1] row_mask:0xf bank_mask:0xf bound_ctrl:1
	s_and_saveexec_b64 s[0:1], vcc
	v_add_f32_e32 v3, v3, v4
	v_add_f32_e32 v1, v1, v2
	v_add_u32_e32 v2, 8, v0
	ds_write2st64_b32 v2, v1, v3 offset1:4
	s_or_b64 exec, exec, s[0:1]
	v_mul_f32_e32 v1, v136, v40
	v_add_f32_e32 v1, v1, v52
	v_add_f32_e32 v2, v53, v48
	v_add_f32_e32 v1, v1, v2
	v_add_f32_dpp v3, v48, v48 quad_perm:[1,0,3,2] row_mask:0xf bank_mask:0xf bound_ctrl:1
	s_nop 0
	v_add_f32_dpp v1, v1, v1 quad_perm:[1,0,3,2] row_mask:0xf bank_mask:0xf bound_ctrl:1
	v_mov_b32_dpp v4, v3 quad_perm:[2,3,0,1] row_mask:0xf bank_mask:0xf bound_ctrl:1
	s_nop 0
	v_mov_b32_dpp v2, v1 quad_perm:[2,3,0,1] row_mask:0xf bank_mask:0xf bound_ctrl:1
	s_and_saveexec_b64 s[0:1], vcc
	v_add_f32_e32 v3, v3, v4
	v_add_f32_e32 v1, v1, v2
	v_add_u32_e32 v2, 16, v0
	ds_write2st64_b32 v2, v1, v3 offset1:4
	s_or_b64 exec, exec, s[0:1]
	v_mul_f32_e32 v3, v139, v40
	v_add_f32_e32 v1, v49, v50
	v_add_f32_e32 v2, v51, v3
	v_add_f32_e32 v1, v1, v2
	v_add_f32_dpp v3, v3, v3 quad_perm:[1,0,3,2] row_mask:0xf bank_mask:0xf bound_ctrl:1
	s_nop 0
	v_add_f32_dpp v1, v1, v1 quad_perm:[1,0,3,2] row_mask:0xf bank_mask:0xf bound_ctrl:1
	v_mov_b32_dpp v4, v3 quad_perm:[2,3,0,1] row_mask:0xf bank_mask:0xf bound_ctrl:1
	s_nop 0
	v_mov_b32_dpp v2, v1 quad_perm:[2,3,0,1] row_mask:0xf bank_mask:0xf bound_ctrl:1
	s_and_saveexec_b64 s[0:1], vcc
	v_add_f32_e32 v3, v3, v4
	v_add_f32_e32 v1, v1, v2
	v_add_u32_e32 v2, 24, v0
	ds_write2st64_b32 v2, v1, v3 offset1:4
	s_or_b64 exec, exec, s[0:1]
	v_mul_f32_e32 v1, v138, v40
	v_add_f32_e32 v1, v1, v62
	v_add_f32_e32 v2, v63, v54
	v_add_f32_e32 v1, v1, v2
	v_add_f32_dpp v3, v54, v54 quad_perm:[1,0,3,2] row_mask:0xf bank_mask:0xf bound_ctrl:1
	s_nop 0
	v_add_f32_dpp v1, v1, v1 quad_perm:[1,0,3,2] row_mask:0xf bank_mask:0xf bound_ctrl:1
	v_mov_b32_dpp v4, v3 quad_perm:[2,3,0,1] row_mask:0xf bank_mask:0xf bound_ctrl:1
	s_nop 0
	v_mov_b32_dpp v2, v1 quad_perm:[2,3,0,1] row_mask:0xf bank_mask:0xf bound_ctrl:1
	s_and_saveexec_b64 s[0:1], vcc
	v_add_f32_e32 v3, v3, v4
	v_add_f32_e32 v1, v1, v2
	v_add_u32_e32 v2, 32, v0
	ds_write2st64_b32 v2, v1, v3 offset1:4
	s_or_b64 exec, exec, s[0:1]
	v_mul_f32_e32 v3, v141, v40
	v_add_f32_e32 v1, v55, v56
	v_add_f32_e32 v2, v57, v3
	v_add_f32_e32 v1, v1, v2
	v_add_f32_dpp v3, v3, v3 quad_perm:[1,0,3,2] row_mask:0xf bank_mask:0xf bound_ctrl:1
	s_nop 0
	v_add_f32_dpp v1, v1, v1 quad_perm:[1,0,3,2] row_mask:0xf bank_mask:0xf bound_ctrl:1
	v_mov_b32_dpp v4, v3 quad_perm:[2,3,0,1] row_mask:0xf bank_mask:0xf bound_ctrl:1
	s_nop 0
	v_mov_b32_dpp v2, v1 quad_perm:[2,3,0,1] row_mask:0xf bank_mask:0xf bound_ctrl:1
	s_and_saveexec_b64 s[0:1], vcc
	v_add_f32_e32 v3, v3, v4
	v_add_f32_e32 v1, v1, v2
	v_add_u32_e32 v2, 40, v0
	ds_write2st64_b32 v2, v1, v3 offset1:4
	s_or_b64 exec, exec, s[0:1]
	v_mul_f32_e32 v1, v140, v40
	v_add_f32_e32 v1, v1, v110
	v_add_f32_e32 v2, v111, v106
	v_add_f32_e32 v1, v1, v2
	v_add_f32_dpp v3, v106, v106 quad_perm:[1,0,3,2] row_mask:0xf bank_mask:0xf bound_ctrl:1
	s_nop 0
	v_add_f32_dpp v1, v1, v1 quad_perm:[1,0,3,2] row_mask:0xf bank_mask:0xf bound_ctrl:1
	v_mov_b32_dpp v4, v3 quad_perm:[2,3,0,1] row_mask:0xf bank_mask:0xf bound_ctrl:1
	s_nop 0
	v_mov_b32_dpp v2, v1 quad_perm:[2,3,0,1] row_mask:0xf bank_mask:0xf bound_ctrl:1
	s_and_saveexec_b64 s[0:1], vcc
	v_add_f32_e32 v3, v3, v4
	v_add_f32_e32 v1, v1, v2
	v_add_u32_e32 v2, 48, v0
	ds_write2st64_b32 v2, v1, v3 offset1:4
	s_or_b64 exec, exec, s[0:1]
	v_mul_f32_e32 v3, v143, v40
	v_add_f32_e32 v1, v107, v108
	v_add_f32_e32 v2, v109, v3
	v_add_f32_e32 v1, v1, v2
	v_add_f32_dpp v3, v3, v3 quad_perm:[1,0,3,2] row_mask:0xf bank_mask:0xf bound_ctrl:1
	s_nop 0
	v_add_f32_dpp v1, v1, v1 quad_perm:[1,0,3,2] row_mask:0xf bank_mask:0xf bound_ctrl:1
	v_mov_b32_dpp v4, v3 quad_perm:[2,3,0,1] row_mask:0xf bank_mask:0xf bound_ctrl:1
	s_nop 0
	v_mov_b32_dpp v2, v1 quad_perm:[2,3,0,1] row_mask:0xf bank_mask:0xf bound_ctrl:1
	s_and_saveexec_b64 s[0:1], vcc
	v_add_f32_e32 v3, v3, v4
	v_add_f32_e32 v1, v1, v2
	v_add_u32_e32 v2, 56, v0
	ds_write2st64_b32 v2, v1, v3 offset1:4
	s_or_b64 exec, exec, s[0:1]
	v_mul_f32_e32 v1, v142, v40
	v_add_f32_e32 v1, v1, v104
	v_add_f32_e32 v2, v105, v100
	v_add_f32_e32 v1, v1, v2
	v_add_f32_dpp v3, v100, v100 quad_perm:[1,0,3,2] row_mask:0xf bank_mask:0xf bound_ctrl:1
	s_nop 0
	v_add_f32_dpp v1, v1, v1 quad_perm:[1,0,3,2] row_mask:0xf bank_mask:0xf bound_ctrl:1
	v_mov_b32_dpp v4, v3 quad_perm:[2,3,0,1] row_mask:0xf bank_mask:0xf bound_ctrl:1
	s_nop 0
	v_mov_b32_dpp v2, v1 quad_perm:[2,3,0,1] row_mask:0xf bank_mask:0xf bound_ctrl:1
	s_and_saveexec_b64 s[0:1], vcc
	v_add_f32_e32 v3, v3, v4
	v_add_f32_e32 v1, v1, v2
	v_add_u32_e32 v2, 64, v0
	ds_write2st64_b32 v2, v1, v3 offset1:4
	s_or_b64 exec, exec, s[0:1]
	v_mul_f32_e32 v3, v145, v40
	v_add_f32_e32 v1, v101, v102
	v_add_f32_e32 v2, v103, v3
	v_add_f32_e32 v1, v1, v2
	v_add_f32_dpp v3, v3, v3 quad_perm:[1,0,3,2] row_mask:0xf bank_mask:0xf bound_ctrl:1
	s_nop 0
	v_add_f32_dpp v1, v1, v1 quad_perm:[1,0,3,2] row_mask:0xf bank_mask:0xf bound_ctrl:1
	v_mov_b32_dpp v4, v3 quad_perm:[2,3,0,1] row_mask:0xf bank_mask:0xf bound_ctrl:1
	s_nop 0
	v_mov_b32_dpp v2, v1 quad_perm:[2,3,0,1] row_mask:0xf bank_mask:0xf bound_ctrl:1
	s_and_saveexec_b64 s[0:1], vcc
	v_add_f32_e32 v3, v3, v4
	v_add_f32_e32 v1, v1, v2
	v_add_u32_e32 v2, 0x48, v0
	ds_write2st64_b32 v2, v1, v3 offset1:4
	s_or_b64 exec, exec, s[0:1]
	v_mul_f32_e32 v1, v144, v40
	v_add_f32_e32 v1, v1, v98
	v_add_f32_e32 v2, v99, v94
	v_add_f32_e32 v1, v1, v2
	v_add_f32_dpp v3, v94, v94 quad_perm:[1,0,3,2] row_mask:0xf bank_mask:0xf bound_ctrl:1
	s_nop 0
	v_add_f32_dpp v1, v1, v1 quad_perm:[1,0,3,2] row_mask:0xf bank_mask:0xf bound_ctrl:1
	v_mov_b32_dpp v4, v3 quad_perm:[2,3,0,1] row_mask:0xf bank_mask:0xf bound_ctrl:1
	s_nop 0
	v_mov_b32_dpp v2, v1 quad_perm:[2,3,0,1] row_mask:0xf bank_mask:0xf bound_ctrl:1
	s_and_saveexec_b64 s[0:1], vcc
	v_add_f32_e32 v3, v3, v4
	v_add_f32_e32 v1, v1, v2
	v_add_u32_e32 v2, 0x50, v0
	ds_write2st64_b32 v2, v1, v3 offset1:4
	s_or_b64 exec, exec, s[0:1]
	v_mul_f32_e32 v3, v150, v40
	v_add_f32_e32 v1, v95, v96
	v_add_f32_e32 v2, v97, v3
	v_add_f32_e32 v1, v1, v2
	v_add_f32_dpp v3, v3, v3 quad_perm:[1,0,3,2] row_mask:0xf bank_mask:0xf bound_ctrl:1
	s_nop 0
	v_add_f32_dpp v1, v1, v1 quad_perm:[1,0,3,2] row_mask:0xf bank_mask:0xf bound_ctrl:1
	v_mov_b32_dpp v4, v3 quad_perm:[2,3,0,1] row_mask:0xf bank_mask:0xf bound_ctrl:1
	s_nop 0
	v_mov_b32_dpp v2, v1 quad_perm:[2,3,0,1] row_mask:0xf bank_mask:0xf bound_ctrl:1
	s_and_saveexec_b64 s[0:1], vcc
	v_add_f32_e32 v3, v3, v4
	v_add_f32_e32 v1, v1, v2
	v_add_u32_e32 v2, 0x58, v0
	ds_write2st64_b32 v2, v1, v3 offset1:4
	s_or_b64 exec, exec, s[0:1]
	v_mul_f32_e32 v1, v148, v40
	v_add_f32_e32 v1, v1, v92
	v_add_f32_e32 v2, v93, v82
	v_add_f32_e32 v1, v1, v2
	v_add_f32_dpp v3, v82, v82 quad_perm:[1,0,3,2] row_mask:0xf bank_mask:0xf bound_ctrl:1
	s_nop 0
	v_add_f32_dpp v1, v1, v1 quad_perm:[1,0,3,2] row_mask:0xf bank_mask:0xf bound_ctrl:1
	v_mov_b32_dpp v4, v3 quad_perm:[2,3,0,1] row_mask:0xf bank_mask:0xf bound_ctrl:1
	s_nop 0
	v_mov_b32_dpp v2, v1 quad_perm:[2,3,0,1] row_mask:0xf bank_mask:0xf bound_ctrl:1
	s_and_saveexec_b64 s[0:1], vcc
	v_add_f32_e32 v3, v3, v4
	v_add_f32_e32 v1, v1, v2
	v_add_u32_e32 v2, 0x60, v0
	ds_write2st64_b32 v2, v1, v3 offset1:4
	s_or_b64 exec, exec, s[0:1]
	v_mul_f32_e32 v3, v149, v40
	v_add_f32_e32 v1, v83, v84
	v_add_f32_e32 v2, v85, v3
	v_add_f32_e32 v1, v1, v2
	v_add_f32_dpp v3, v3, v3 quad_perm:[1,0,3,2] row_mask:0xf bank_mask:0xf bound_ctrl:1
	s_nop 0
	v_add_f32_dpp v1, v1, v1 quad_perm:[1,0,3,2] row_mask:0xf bank_mask:0xf bound_ctrl:1
	v_mov_b32_dpp v4, v3 quad_perm:[2,3,0,1] row_mask:0xf bank_mask:0xf bound_ctrl:1
	s_nop 0
	v_mov_b32_dpp v2, v1 quad_perm:[2,3,0,1] row_mask:0xf bank_mask:0xf bound_ctrl:1
	s_and_saveexec_b64 s[0:1], vcc
	v_add_f32_e32 v3, v3, v4
	v_add_f32_e32 v1, v1, v2
	v_add_u32_e32 v2, 0x68, v0
	ds_write2st64_b32 v2, v1, v3 offset1:4
	s_or_b64 exec, exec, s[0:1]
	v_mul_f32_e32 v1, v146, v40
	v_add_f32_e32 v1, v1, v80
	v_add_f32_e32 v2, v81, v58
	v_add_f32_e32 v1, v1, v2
	v_add_f32_dpp v3, v58, v58 quad_perm:[1,0,3,2] row_mask:0xf bank_mask:0xf bound_ctrl:1
	s_nop 0
	v_add_f32_dpp v1, v1, v1 quad_perm:[1,0,3,2] row_mask:0xf bank_mask:0xf bound_ctrl:1
	v_mov_b32_dpp v4, v3 quad_perm:[2,3,0,1] row_mask:0xf bank_mask:0xf bound_ctrl:1
	s_nop 0
	v_mov_b32_dpp v2, v1 quad_perm:[2,3,0,1] row_mask:0xf bank_mask:0xf bound_ctrl:1
	s_and_saveexec_b64 s[0:1], vcc
	v_add_f32_e32 v3, v3, v4
	v_add_f32_e32 v1, v1, v2
	v_add_u32_e32 v2, 0x70, v0
	ds_write2st64_b32 v2, v1, v3 offset1:4
	s_or_b64 exec, exec, s[0:1]
	v_mul_f32_e32 v3, v147, v40
	v_add_f32_e32 v1, v59, v60
	v_add_f32_e32 v2, v61, v3
	v_add_f32_e32 v1, v1, v2
	v_add_f32_dpp v3, v3, v3 quad_perm:[1,0,3,2] row_mask:0xf bank_mask:0xf bound_ctrl:1
	s_nop 0
	v_add_f32_dpp v1, v1, v1 quad_perm:[1,0,3,2] row_mask:0xf bank_mask:0xf bound_ctrl:1
	v_mov_b32_dpp v4, v3 quad_perm:[2,3,0,1] row_mask:0xf bank_mask:0xf bound_ctrl:1
	s_nop 0
	v_mov_b32_dpp v2, v1 quad_perm:[2,3,0,1] row_mask:0xf bank_mask:0xf bound_ctrl:1
	s_and_saveexec_b64 s[0:1], vcc
	v_add_f32_e32 v3, v3, v4
	v_add_f32_e32 v1, v1, v2
	v_add_u32_e32 v0, 0x78, v0
	ds_write2st64_b32 v0, v1, v3 offset1:4
	s_or_b64 exec, exec, s[0:1]
	s_waitcnt lgkmcnt(0)
	v_lshl_add_u32 v6, v125, 2, s89
	ds_read_b32 v1, v6
	v_cmp_eq_u32_e32 vcc, 0, v128
	v_cmp_ne_u32_e64 s[0:1], 0, v128
	v_mov_b32_e32 v0, 0
	v_mov_b32_e32 v2, 0
	s_and_saveexec_b64 s[4:5], s[0:1]
	ds_read_b32 v2, v6 offset:1020
	s_or_b64 exec, exec, s[4:5]
	v_add_u32_e32 v3, s78, v133
	v_ashrrev_i32_e32 v4, 6, v3
	s_waitcnt lgkmcnt(0)
	v_add_f32_e32 v1, v1, v2
	v_cmp_eq_u32_e64 s[4:5], v128, v4
	v_add_u32_e32 v2, -1, v4
	s_or_b64 s[8:9], vcc, s[4:5]
	v_cmp_eq_u32_e64 s[4:5], v128, v2
	v_lshlrev_b32_e32 v7, 6, v128
	s_or_b64 s[4:5], s[8:9], s[4:5]
	v_cndmask_b32_e64 v1, v1, v212, s[4:5]
	v_cmp_le_i32_e64 s[4:5], v7, v3
	v_mov_b32_e32 v2, 0xff800000
	s_nop 0
	v_cndmask_b32_e64 v1, v2, v1, s[4:5]
	ds_write_b32 v6, v1 offset:2048
	v_add_u32_e32 v1, 2, v133
	v_lshlrev_b32_e32 v4, 5, v1
	v_or_b32_e32 v2, v4, v128
	v_lshl_add_u32 v5, v2, 2, s89
	ds_read_b32 v2, v5
	s_and_saveexec_b64 s[4:5], s[0:1]
	ds_read_b32 v0, v5 offset:1020
	s_or_b64 exec, exec, s[4:5]
	v_add_u32_e32 v1, s78, v1
	v_ashrrev_i32_e32 v3, 6, v1
	s_waitcnt lgkmcnt(0)
	v_add_f32_e32 v0, v2, v0
	v_cmp_eq_u32_e64 s[4:5], v128, v3
	v_add_u32_e32 v2, -1, v3
	s_or_b64 s[8:9], vcc, s[4:5]
	v_cmp_eq_u32_e64 s[4:5], v128, v2
	s_or_b64 s[4:5], s[8:9], s[4:5]
	v_mov_b32_e32 v8, 0
	v_cndmask_b32_e64 v0, v0, v212, s[4:5]
	v_cmp_le_i32_e64 s[4:5], v7, v1
	v_mov_b32_e32 v1, 0xff800000
	v_mov_b32_e32 v9, 0
	v_cndmask_b32_e64 v0, v1, v0, s[4:5]
	ds_write_b32 v5, v0 offset:2048
	v_add_u32_e32 v0, 4, v133
	v_lshlrev_b32_e32 v2, 5, v0
	v_or_b32_e32 v1, v2, v128
	v_lshl_add_u32 v3, v1, 2, s89
	ds_read_b32 v1, v3
	s_and_saveexec_b64 s[4:5], s[0:1]
	ds_read_b32 v9, v3 offset:1020
	s_or_b64 exec, exec, s[4:5]
	v_add_u32_e32 v0, s78, v0
	v_ashrrev_i32_e32 v10, 6, v0
	s_waitcnt lgkmcnt(0)
	v_add_f32_e32 v1, v1, v9
	v_cmp_eq_u32_e64 s[4:5], v128, v10
	v_add_u32_e32 v9, -1, v10
	s_or_b64 s[8:9], vcc, s[4:5]
	v_cmp_eq_u32_e64 s[4:5], v128, v9
	s_or_b64 s[4:5], s[8:9], s[4:5]
	v_add_u32_e32 v9, 6, v133
	v_cndmask_b32_e64 v1, v1, v212, s[4:5]
	v_cmp_le_i32_e64 s[4:5], v7, v0
	v_mov_b32_e32 v0, 0xff800000
	s_nop 0
	v_cndmask_b32_e64 v0, v0, v1, s[4:5]
	ds_write_b32 v3, v0 offset:2048
	v_lshlrev_b32_e32 v0, 5, v9
	v_or_b32_e32 v1, v0, v128
	v_lshl_add_u32 v1, v1, 2, s89
	ds_read_b32 v10, v1
	s_and_saveexec_b64 s[4:5], s[0:1]
	ds_read_b32 v8, v1 offset:1020
	s_or_b64 exec, exec, s[4:5]
	v_add_u32_e32 v9, s78, v9
	v_ashrrev_i32_e32 v11, 6, v9
	s_waitcnt lgkmcnt(0)
	v_add_f32_e32 v8, v10, v8
	v_cmp_eq_u32_e64 s[0:1], v128, v11
	v_add_u32_e32 v10, -1, v11
	s_or_b64 s[0:1], vcc, s[0:1]
	v_cmp_eq_u32_e32 vcc, v128, v10
	s_or_b64 vcc, s[0:1], vcc
	v_and_b32_e32 v12, 0x3fffffe0, v125
	v_cndmask_b32_e32 v8, v8, v212, vcc
	v_cmp_le_i32_e32 vcc, v7, v9
	v_mov_b32_e32 v7, 0xff800000
	v_lshl_add_u32 v22, v12, 2, s89
	v_cndmask_b32_e32 v7, v7, v8, vcc
	ds_write_b32 v1, v7 offset:2048
	s_waitcnt lgkmcnt(0)
	ds_read_b32 v23, v6 offset:2048
	ds_read_b128 v[6:9], v22 offset:2048
	v_cmp_ne_u32_e64 s[0:1], 0, v128
	v_cmp_lt_u32_e64 s[66:67], 1, v128
	ds_read_b128 v[10:13], v22 offset:2064
	ds_read_b128 v[14:17], v22 offset:2080
	ds_read_b128 v[18:21], v22 offset:2096
	v_cmp_eq_u32_e32 vcc, 0, v125
	s_waitcnt lgkmcnt(3)
	v_cmp_eq_f32_e64 s[8:9], v6, v23
	v_cmp_gt_f32_e64 s[4:5], v6, v23
	s_and_b64 s[8:9], s[0:1], s[8:9]
	s_or_b64 s[4:5], s[4:5], s[8:9]
	v_cmp_eq_f32_e64 s[8:9], v7, v23
	v_cndmask_b32_e64 v6, 0, 1, s[4:5]
	v_cmp_gt_f32_e64 s[4:5], v7, v23
	s_and_b64 s[8:9], s[8:9], s[66:67]
	s_or_b64 s[4:5], s[4:5], s[8:9]
	v_cndmask_b32_e64 v7, 0, 1, s[4:5]
	v_cmp_eq_f32_e64 s[10:11], v8, v23
	v_cmp_lt_u32_e64 s[4:5], 2, v128
	v_cmp_gt_f32_e64 s[8:9], v8, v23
	s_and_b64 s[10:11], s[10:11], s[4:5]
	s_or_b64 s[8:9], s[8:9], s[10:11]
	v_addc_co_u32_e64 v6, s[8:9], v7, v6, s[8:9]
	v_cmp_eq_f32_e64 s[12:13], v9, v23
	v_cmp_lt_u32_e64 s[8:9], 3, v128
	v_cmp_gt_f32_e64 s[10:11], v9, v23
	s_and_b64 s[12:13], s[12:13], s[8:9]
	s_or_b64 s[10:11], s[10:11], s[12:13]
	v_cndmask_b32_e64 v7, 0, 1, s[10:11]
	s_waitcnt lgkmcnt(2)
	v_cmp_eq_f32_e64 s[14:15], v10, v23
	v_cmp_lt_u32_e64 s[10:11], 4, v128
	v_cmp_gt_f32_e64 s[12:13], v10, v23
	s_and_b64 s[14:15], s[14:15], s[10:11]
	s_or_b64 s[12:13], s[12:13], s[14:15]
	v_addc_co_u32_e64 v6, s[12:13], v6, v7, s[12:13]
	v_cmp_eq_f32_e64 s[16:17], v11, v23
	v_cmp_lt_u32_e64 s[12:13], 5, v128
	v_cmp_gt_f32_e64 s[14:15], v11, v23
	s_and_b64 s[16:17], s[16:17], s[12:13]
	s_or_b64 s[14:15], s[14:15], s[16:17]
	v_cndmask_b32_e64 v7, 0, 1, s[14:15]
	v_cmp_eq_f32_e64 s[18:19], v12, v23
	v_cmp_lt_u32_e64 s[14:15], 6, v128
	v_cmp_gt_f32_e64 s[16:17], v12, v23
	s_and_b64 s[18:19], s[18:19], s[14:15]
	s_or_b64 s[16:17], s[16:17], s[18:19]
	v_addc_co_u32_e64 v6, s[16:17], v6, v7, s[16:17]
	v_cmp_eq_f32_e64 s[20:21], v13, v23
	v_cmp_lt_u32_e64 s[16:17], 7, v128
	v_cmp_gt_f32_e64 s[18:19], v13, v23
	s_and_b64 s[20:21], s[20:21], s[16:17]
	s_or_b64 s[18:19], s[18:19], s[20:21]
	v_cndmask_b32_e64 v7, 0, 1, s[18:19]
	s_waitcnt lgkmcnt(1)
	v_cmp_eq_f32_e64 s[22:23], v14, v23
	v_cmp_lt_u32_e64 s[18:19], 8, v128
	v_cmp_gt_f32_e64 s[20:21], v14, v23
	s_and_b64 s[22:23], s[22:23], s[18:19]
	s_or_b64 s[20:21], s[20:21], s[22:23]
	v_addc_co_u32_e64 v6, s[20:21], v6, v7, s[20:21]
	v_cmp_eq_f32_e64 s[24:25], v15, v23
	v_cmp_lt_u32_e64 s[20:21], 9, v128
	v_cmp_gt_f32_e64 s[22:23], v15, v23
	s_and_b64 s[24:25], s[24:25], s[20:21]
	s_or_b64 s[22:23], s[22:23], s[24:25]
	v_cndmask_b32_e64 v7, 0, 1, s[22:23]
	v_cmp_eq_f32_e64 s[26:27], v16, v23
	v_cmp_lt_u32_e64 s[22:23], 10, v128
	v_cmp_gt_f32_e64 s[24:25], v16, v23
	s_and_b64 s[26:27], s[26:27], s[22:23]
	s_or_b64 s[24:25], s[24:25], s[26:27]
	v_addc_co_u32_e64 v10, s[24:25], v6, v7, s[24:25]
	v_cmp_eq_f32_e64 s[28:29], v17, v23
	v_cmp_lt_u32_e64 s[24:25], 11, v128
	v_cmp_gt_f32_e64 s[26:27], v17, v23
	s_and_b64 s[28:29], s[28:29], s[24:25]
	s_or_b64 s[26:27], s[26:27], s[28:29]
	s_waitcnt lgkmcnt(0)
	v_cmp_eq_f32_e64 s[30:31], v18, v23
	v_cmp_lt_u32_e64 s[28:29], 12, v128
	v_cndmask_b32_e64 v11, 0, 1, s[26:27]
	v_cmp_gt_f32_e64 s[26:27], v18, v23
	s_and_b64 s[30:31], s[30:31], s[28:29]
	s_or_b64 s[26:27], s[26:27], s[30:31]
	v_addc_co_u32_e64 v10, s[26:27], v10, v11, s[26:27]
	v_cmp_eq_f32_e64 s[34:35], v19, v23
	v_cmp_lt_u32_e64 s[30:31], 13, v128
	v_cmp_gt_f32_e64 s[26:27], v19, v23
	s_and_b64 s[34:35], s[34:35], s[30:31]
	ds_read_b128 v[6:9], v22 offset:2112
	s_or_b64 s[26:27], s[26:27], s[34:35]
	v_cmp_eq_f32_e64 s[36:37], v20, v23
	v_cmp_lt_u32_e64 s[34:35], 14, v128
	v_cndmask_b32_e64 v11, 0, 1, s[26:27]
	v_cmp_gt_f32_e64 s[26:27], v20, v23
	s_and_b64 s[36:37], s[36:37], s[34:35]
	s_or_b64 s[26:27], s[26:27], s[36:37]
	v_addc_co_u32_e64 v10, s[26:27], v10, v11, s[26:27]
	v_cmp_eq_f32_e64 s[38:39], v21, v23
	v_cmp_lt_u32_e64 s[36:37], 15, v128
	v_cmp_gt_f32_e64 s[26:27], v21, v23
	s_and_b64 s[38:39], s[38:39], s[36:37]
	s_or_b64 s[26:27], s[26:27], s[38:39]
	s_waitcnt lgkmcnt(0)
	v_cmp_eq_f32_e64 s[40:41], v6, v23
	v_cmp_lt_u32_e64 s[38:39], 16, v128
	v_cndmask_b32_e64 v11, 0, 1, s[26:27]
	v_cmp_gt_f32_e64 s[26:27], v6, v23
	s_and_b64 s[40:41], s[40:41], s[38:39]
	s_or_b64 s[26:27], s[26:27], s[40:41]
	v_addc_co_u32_e64 v6, s[26:27], v10, v11, s[26:27]
	v_cmp_eq_f32_e64 s[42:43], v7, v23
	v_cmp_lt_u32_e64 s[40:41], 17, v128
	v_cmp_gt_f32_e64 s[26:27], v7, v23
	s_and_b64 s[42:43], s[42:43], s[40:41]
	s_or_b64 s[26:27], s[26:27], s[42:43]
	v_cmp_eq_f32_e64 s[44:45], v8, v23
	v_cmp_lt_u32_e64 s[42:43], 18, v128
	v_cndmask_b32_e64 v7, 0, 1, s[26:27]
	v_cmp_gt_f32_e64 s[26:27], v8, v23
	s_and_b64 s[44:45], s[44:45], s[42:43]
	s_or_b64 s[26:27], s[26:27], s[44:45]
	v_addc_co_u32_e64 v14, s[26:27], v6, v7, s[26:27]
	v_cmp_gt_f32_e64 s[44:45], v9, v23
	v_cmp_eq_f32_e64 s[46:47], v9, v23
	ds_read_b128 v[6:9], v22 offset:2128
	ds_read_b128 v[10:13], v22 offset:2144
	v_cmp_lt_u32_e64 s[26:27], 19, v128
	s_and_b64 s[46:47], s[46:47], s[26:27]
	s_or_b64 s[44:45], s[44:45], s[46:47]
	s_waitcnt lgkmcnt(1)
	v_cmp_eq_f32_e64 s[48:49], v6, v23
	v_cmp_lt_u32_e64 s[46:47], 20, v128
	v_cndmask_b32_e64 v15, 0, 1, s[44:45]
	v_cmp_gt_f32_e64 s[44:45], v6, v23
	s_and_b64 s[48:49], s[48:49], s[46:47]
	s_or_b64 s[44:45], s[44:45], s[48:49]
	v_addc_co_u32_e64 v6, s[44:45], v14, v15, s[44:45]
	v_cmp_eq_f32_e64 s[50:51], v7, v23
	v_cmp_lt_u32_e64 s[48:49], 21, v128
	v_cmp_gt_f32_e64 s[44:45], v7, v23
	s_and_b64 s[50:51], s[50:51], s[48:49]
	s_or_b64 s[44:45], s[44:45], s[50:51]
	v_cmp_eq_f32_e64 s[52:53], v8, v23
	v_cmp_lt_u32_e64 s[50:51], 22, v128
	v_cndmask_b32_e64 v7, 0, 1, s[44:45]
	v_cmp_gt_f32_e64 s[44:45], v8, v23
	s_and_b64 s[52:53], s[52:53], s[50:51]
	s_or_b64 s[44:45], s[44:45], s[52:53]
	v_addc_co_u32_e64 v6, s[44:45], v6, v7, s[44:45]
	v_cmp_eq_f32_e64 s[54:55], v9, v23
	v_cmp_lt_u32_e64 s[52:53], 23, v128
	v_cmp_gt_f32_e64 s[44:45], v9, v23
	s_and_b64 s[54:55], s[54:55], s[52:53]
	s_or_b64 s[44:45], s[44:45], s[54:55]
	s_waitcnt lgkmcnt(0)
	v_cmp_eq_f32_e64 s[56:57], v10, v23
	v_cmp_lt_u32_e64 s[54:55], 24, v128
	v_cndmask_b32_e64 v7, 0, 1, s[44:45]
	v_cmp_gt_f32_e64 s[44:45], v10, v23
	s_and_b64 s[56:57], s[56:57], s[54:55]
	s_or_b64 s[44:45], s[44:45], s[56:57]
	v_addc_co_u32_e64 v6, s[44:45], v6, v7, s[44:45]
	v_cmp_eq_f32_e64 s[58:59], v11, v23
	v_cmp_lt_u32_e64 s[56:57], 25, v128
	v_cmp_gt_f32_e64 s[44:45], v11, v23
	s_and_b64 s[58:59], s[58:59], s[56:57]
	s_or_b64 s[44:45], s[44:45], s[58:59]
	v_cmp_eq_f32_e64 s[60:61], v12, v23
	v_cmp_lt_u32_e64 s[58:59], 26, v128
	v_cndmask_b32_e64 v7, 0, 1, s[44:45]
	v_cmp_gt_f32_e64 s[44:45], v12, v23
	s_and_b64 s[60:61], s[60:61], s[58:59]
	s_or_b64 s[44:45], s[44:45], s[60:61]
	v_addc_co_u32_e64 v9, s[44:45], v6, v7, s[44:45]
	ds_read_b96 v[6:8], v22 offset:2160
	v_cmp_eq_f32_e64 s[62:63], v13, v23
	v_cmp_lt_u32_e64 s[44:45], 27, v128
	v_mov_b32_e32 v11, 0x7c
	v_cmp_gt_f32_e64 s[60:61], v13, v23
	s_and_b64 s[62:63], s[62:63], s[44:45]
	v_lshl_or_b32 v11, v125, 2, v11
	s_or_b64 s[60:61], s[60:61], s[62:63]
	v_add_u32_e32 v11, s89, v11
	v_cndmask_b32_e64 v10, 0, 1, s[60:61]
	ds_read_b32 v11, v11 offset:2048
	s_waitcnt lgkmcnt(1)
	v_cmp_eq_f32_e64 s[64:65], v6, v23
	v_cmp_lt_u32_e64 s[60:61], 28, v128
	v_cmp_gt_f32_e64 s[62:63], v6, v23
	s_and_b64 s[64:65], s[64:65], s[60:61]
	s_or_b64 s[62:63], s[62:63], s[64:65]
	v_addc_co_u32_e64 v6, s[62:63], v9, v10, s[62:63]
	v_cmp_eq_f32_e64 s[68:69], v7, v23
	v_cmp_lt_u32_e64 s[62:63], 29, v128
	v_cmp_gt_f32_e64 s[64:65], v7, v23
	s_and_b64 s[68:69], s[68:69], s[62:63]
	s_or_b64 s[64:65], s[64:65], s[68:69]
	v_cndmask_b32_e64 v7, 0, 1, s[64:65]
	v_cmp_eq_f32_e64 s[70:71], v8, v23
	v_cmp_eq_u32_e64 s[64:65], 31, v128
	v_cmp_gt_f32_e64 s[68:69], v8, v23
	s_and_b64 s[86:87], s[64:65], s[70:71]
	s_waitcnt lgkmcnt(0)
	v_cmp_gt_f32_e64 s[70:71], v11, v23
	v_add_u32_e32 v6, v6, v7
	s_or_b64 s[68:69], s[68:69], s[86:87]
	v_cndmask_b32_e64 v7, 0, 1, s[70:71]
	v_addc_co_u32_e64 v6, s[68:69], v6, v7, s[68:69]
	v_cmp_gt_u32_e64 s[70:71], 16, v6
	s_and_saveexec_b64 s[68:69], vcc
	v_mov_b32_e32 v6, s89
	v_mov_b64_e32 v[8:9], s[70:71]
	ds_write_b64 v6, v[8:9] offset:3072
	s_or_b64 exec, exec, s[68:69]
	v_lshl_add_u32 v20, v4, 2, s89
	ds_read_b32 v21, v5 offset:2048
	ds_read_b128 v[4:7], v20 offset:2048
	ds_read_b128 v[8:11], v20 offset:2064
	ds_read_b128 v[12:15], v20 offset:2080
	ds_read_b128 v[16:19], v20 offset:2096
	s_waitcnt lgkmcnt(3)
	v_cmp_eq_f32_e64 s[70:71], v4, v21
	v_cmp_gt_f32_e64 s[68:69], v4, v21
	s_and_b64 s[70:71], s[0:1], s[70:71]
	s_or_b64 s[68:69], s[68:69], s[70:71]
	v_cmp_eq_f32_e64 s[70:71], v5, v21
	v_cndmask_b32_e64 v4, 0, 1, s[68:69]
	v_cmp_gt_f32_e64 s[68:69], v5, v21
	s_and_b64 s[70:71], s[70:71], s[66:67]
	s_or_b64 s[68:69], s[68:69], s[70:71]
	v_cmp_eq_f32_e64 s[70:71], v6, v21
	v_cndmask_b32_e64 v5, 0, 1, s[68:69]
	v_cmp_gt_f32_e64 s[68:69], v6, v21
	s_and_b64 s[70:71], s[70:71], s[4:5]
	s_or_b64 s[68:69], s[68:69], s[70:71]
	v_cmp_eq_f32_e64 s[70:71], v7, v21
	v_cndmask_b32_e64 v6, 0, 1, s[68:69]
	v_cmp_gt_f32_e64 s[68:69], v7, v21
	s_and_b64 s[70:71], s[70:71], s[8:9]
	s_or_b64 s[68:69], s[68:69], s[70:71]
	s_waitcnt lgkmcnt(2)
	v_cmp_eq_f32_e64 s[70:71], v8, v21
	v_add3_u32 v4, v5, v4, v6
	v_cndmask_b32_e64 v5, 0, 1, s[68:69]
	v_cmp_gt_f32_e64 s[68:69], v8, v21
	s_and_b64 s[70:71], s[70:71], s[10:11]
	s_or_b64 s[68:69], s[68:69], s[70:71]
	v_cmp_eq_f32_e64 s[70:71], v9, v21
	v_cndmask_b32_e64 v6, 0, 1, s[68:69]
	v_cmp_gt_f32_e64 s[68:69], v9, v21
	s_and_b64 s[70:71], s[70:71], s[12:13]
	s_or_b64 s[68:69], s[68:69], s[70:71]
	v_cmp_eq_f32_e64 s[70:71], v10, v21
	v_add3_u32 v4, v4, v5, v6
	v_cndmask_b32_e64 v5, 0, 1, s[68:69]
	v_cmp_gt_f32_e64 s[68:69], v10, v21
	s_and_b64 s[70:71], s[70:71], s[14:15]
	s_or_b64 s[68:69], s[68:69], s[70:71]
	v_cmp_eq_f32_e64 s[70:71], v11, v21
	v_cndmask_b32_e64 v6, 0, 1, s[68:69]
	v_cmp_gt_f32_e64 s[68:69], v11, v21
	s_and_b64 s[70:71], s[70:71], s[16:17]
	s_or_b64 s[68:69], s[68:69], s[70:71]
	s_waitcnt lgkmcnt(1)
	v_cmp_eq_f32_e64 s[70:71], v12, v21
	v_add3_u32 v4, v4, v5, v6
	v_cndmask_b32_e64 v5, 0, 1, s[68:69]
	v_cmp_gt_f32_e64 s[68:69], v12, v21
	s_and_b64 s[70:71], s[70:71], s[18:19]
	s_or_b64 s[68:69], s[68:69], s[70:71]
	v_cmp_eq_f32_e64 s[70:71], v13, v21
	v_cndmask_b32_e64 v6, 0, 1, s[68:69]
	v_cmp_gt_f32_e64 s[68:69], v13, v21
	s_and_b64 s[70:71], s[70:71], s[20:21]
	s_or_b64 s[68:69], s[68:69], s[70:71]
	v_cmp_eq_f32_e64 s[70:71], v14, v21
	v_add3_u32 v4, v4, v5, v6
	v_cndmask_b32_e64 v5, 0, 1, s[68:69]
	v_cmp_gt_f32_e64 s[68:69], v14, v21
	s_and_b64 s[70:71], s[70:71], s[22:23]
	s_or_b64 s[68:69], s[68:69], s[70:71]
	v_cmp_eq_f32_e64 s[70:71], v15, v21
	v_cndmask_b32_e64 v6, 0, 1, s[68:69]
	v_cmp_gt_f32_e64 s[68:69], v15, v21
	s_and_b64 s[70:71], s[70:71], s[24:25]
	s_or_b64 s[68:69], s[68:69], s[70:71]
	s_waitcnt lgkmcnt(0)
	v_cmp_eq_f32_e64 s[70:71], v16, v21
	v_cndmask_b32_e64 v9, 0, 1, s[68:69]
	v_cmp_gt_f32_e64 s[68:69], v16, v21
	s_and_b64 s[70:71], s[70:71], s[28:29]
	s_or_b64 s[68:69], s[68:69], s[70:71]
	v_cmp_eq_f32_e64 s[70:71], v17, v21
	v_add3_u32 v8, v4, v5, v6
	ds_read_b128 v[4:7], v20 offset:2112
	v_cndmask_b32_e64 v10, 0, 1, s[68:69]
	v_cmp_gt_f32_e64 s[68:69], v17, v21
	s_and_b64 s[70:71], s[70:71], s[30:31]
	s_or_b64 s[68:69], s[68:69], s[70:71]
	v_cmp_eq_f32_e64 s[70:71], v18, v21
	v_add3_u32 v8, v8, v9, v10
	v_cndmask_b32_e64 v9, 0, 1, s[68:69]
	v_cmp_gt_f32_e64 s[68:69], v18, v21
	s_and_b64 s[70:71], s[70:71], s[34:35]
	s_or_b64 s[68:69], s[68:69], s[70:71]
	v_cmp_eq_f32_e64 s[70:71], v19, v21
	v_cndmask_b32_e64 v10, 0, 1, s[68:69]
	v_cmp_gt_f32_e64 s[68:69], v19, v21
	s_and_b64 s[70:71], s[70:71], s[36:37]
	s_or_b64 s[68:69], s[68:69], s[70:71]
	s_waitcnt lgkmcnt(0)
	v_cmp_eq_f32_e64 s[70:71], v4, v21
	v_add3_u32 v8, v8, v9, v10
	v_cndmask_b32_e64 v9, 0, 1, s[68:69]
	v_cmp_gt_f32_e64 s[68:69], v4, v21
	s_and_b64 s[70:71], s[70:71], s[38:39]
	s_or_b64 s[68:69], s[68:69], s[70:71]
	v_cmp_eq_f32_e64 s[70:71], v5, v21
	v_cndmask_b32_e64 v4, 0, 1, s[68:69]
	v_cmp_gt_f32_e64 s[68:69], v5, v21
	s_and_b64 s[70:71], s[70:71], s[40:41]
	s_or_b64 s[68:69], s[68:69], s[70:71]
	v_cmp_eq_f32_e64 s[70:71], v6, v21
	v_cndmask_b32_e64 v5, 0, 1, s[68:69]
	v_cmp_gt_f32_e64 s[68:69], v6, v21
	s_and_b64 s[70:71], s[70:71], s[42:43]
	s_or_b64 s[68:69], s[68:69], s[70:71]
	v_add3_u32 v4, v8, v9, v4
	v_cndmask_b32_e64 v6, 0, 1, s[68:69]
	v_add3_u32 v12, v4, v5, v6
	v_cmp_gt_f32_e64 s[68:69], v7, v21
	v_cmp_eq_f32_e64 s[70:71], v7, v21
	ds_read_b128 v[4:7], v20 offset:2128
	ds_read_b128 v[8:11], v20 offset:2144
	s_and_b64 s[70:71], s[70:71], s[26:27]
	s_or_b64 s[68:69], s[68:69], s[70:71]
	v_cndmask_b32_e64 v13, 0, 1, s[68:69]
	s_waitcnt lgkmcnt(1)
	v_cmp_eq_f32_e64 s[70:71], v4, v21
	v_cmp_gt_f32_e64 s[68:69], v4, v21
	s_and_b64 s[70:71], s[70:71], s[46:47]
	s_or_b64 s[68:69], s[68:69], s[70:71]
	v_cmp_eq_f32_e64 s[70:71], v5, v21
	v_cndmask_b32_e64 v4, 0, 1, s[68:69]
	v_cmp_gt_f32_e64 s[68:69], v5, v21
	s_and_b64 s[70:71], s[70:71], s[48:49]
	s_or_b64 s[68:69], s[68:69], s[70:71]
	v_cmp_eq_f32_e64 s[70:71], v6, v21
	v_cndmask_b32_e64 v5, 0, 1, s[68:69]
	v_cmp_gt_f32_e64 s[68:69], v6, v21
	s_and_b64 s[70:71], s[70:71], s[50:51]
	s_or_b64 s[68:69], s[68:69], s[70:71]
	v_cmp_eq_f32_e64 s[70:71], v7, v21
	v_cndmask_b32_e64 v6, 0, 1, s[68:69]
	v_cmp_gt_f32_e64 s[68:69], v7, v21
	s_and_b64 s[70:71], s[70:71], s[52:53]
	v_add3_u32 v4, v12, v13, v4
	s_or_b64 s[68:69], s[68:69], s[70:71]
	s_waitcnt lgkmcnt(0)
	v_cmp_eq_f32_e64 s[70:71], v8, v21
	v_add3_u32 v4, v4, v5, v6
	v_cndmask_b32_e64 v5, 0, 1, s[68:69]
	v_cmp_gt_f32_e64 s[68:69], v8, v21
	s_and_b64 s[70:71], s[70:71], s[54:55]
	s_or_b64 s[68:69], s[68:69], s[70:71]
	v_cmp_eq_f32_e64 s[70:71], v9, v21
	v_cndmask_b32_e64 v6, 0, 1, s[68:69]
	v_cmp_gt_f32_e64 s[68:69], v9, v21
	s_and_b64 s[70:71], s[70:71], s[56:57]
	s_or_b64 s[68:69], s[68:69], s[70:71]
	v_cmp_eq_f32_e64 s[70:71], v10, v21
	v_add3_u32 v4, v4, v5, v6
	v_cndmask_b32_e64 v5, 0, 1, s[68:69]
	v_cmp_gt_f32_e64 s[68:69], v10, v21
	s_and_b64 s[70:71], s[70:71], s[58:59]
	s_or_b64 s[68:69], s[68:69], s[70:71]
	v_cndmask_b32_e64 v6, 0, 1, s[68:69]
	v_add3_u32 v8, v4, v5, v6
	ds_read_b128 v[4:7], v20 offset:2160
	v_cmp_eq_f32_e64 s[70:71], v11, v21
	v_cmp_gt_f32_e64 s[68:69], v11, v21
	s_and_b64 s[70:71], s[70:71], s[44:45]
	s_or_b64 s[68:69], s[68:69], s[70:71]
	s_waitcnt lgkmcnt(0)
	v_cmp_eq_f32_e64 s[70:71], v4, v21
	v_cndmask_b32_e64 v9, 0, 1, s[68:69]
	v_cmp_gt_f32_e64 s[68:69], v4, v21
	s_and_b64 s[70:71], s[70:71], s[60:61]
	s_or_b64 s[68:69], s[68:69], s[70:71]
	v_cmp_eq_f32_e64 s[70:71], v5, v21
	v_cndmask_b32_e64 v4, 0, 1, s[68:69]
	v_cmp_gt_f32_e64 s[68:69], v5, v21
	s_and_b64 s[70:71], s[70:71], s[62:63]
	s_or_b64 s[68:69], s[68:69], s[70:71]
	v_cmp_eq_f32_e64 s[70:71], v6, v21
	v_cndmask_b32_e64 v5, 0, 1, s[68:69]
	v_cmp_gt_f32_e64 s[68:69], v6, v21
	s_and_b64 s[70:71], s[64:65], s[70:71]
	s_or_b64 s[68:69], s[68:69], s[70:71]
	v_add3_u32 v4, v8, v9, v4
	v_cndmask_b32_e64 v6, 0, 1, s[68:69]
	v_cmp_gt_f32_e64 s[68:69], v7, v21
	s_nop 1
	v_addc_co_u32_e64 v4, s[68:69], v4, v5, s[68:69]
	v_add_u32_e32 v4, v4, v6
	v_cmp_gt_u32_e64 s[70:71], 16, v4
	s_and_saveexec_b64 s[68:69], vcc
	v_mov_b32_e32 v4, s89
	v_mov_b64_e32 v[6:7], s[70:71]
	ds_write_b64 v4, v[6:7] offset:3080
	s_or_b64 exec, exec, s[68:69]
	v_lshl_add_u32 v18, v2, 2, s89
	ds_read_b32 v19, v3 offset:2048
	ds_read_b128 v[2:5], v18 offset:2048
	ds_read_b128 v[6:9], v18 offset:2064
	ds_read_b128 v[10:13], v18 offset:2080
	ds_read_b128 v[14:17], v18 offset:2096
	s_waitcnt lgkmcnt(3)
	v_cmp_eq_f32_e64 s[70:71], v2, v19
	v_cmp_gt_f32_e64 s[68:69], v2, v19
	s_and_b64 s[70:71], s[0:1], s[70:71]
	s_or_b64 s[68:69], s[68:69], s[70:71]
	v_cmp_eq_f32_e64 s[70:71], v3, v19
	v_cndmask_b32_e64 v2, 0, 1, s[68:69]
	v_cmp_gt_f32_e64 s[68:69], v3, v19
	s_and_b64 s[70:71], s[70:71], s[66:67]
	s_or_b64 s[68:69], s[68:69], s[70:71]
	v_cmp_eq_f32_e64 s[70:71], v4, v19
	v_cndmask_b32_e64 v3, 0, 1, s[68:69]
	v_cmp_gt_f32_e64 s[68:69], v4, v19
	s_and_b64 s[70:71], s[70:71], s[4:5]
	s_or_b64 s[68:69], s[68:69], s[70:71]
	v_cmp_eq_f32_e64 s[70:71], v5, v19
	v_cndmask_b32_e64 v4, 0, 1, s[68:69]
	v_cmp_gt_f32_e64 s[68:69], v5, v19
	s_and_b64 s[70:71], s[70:71], s[8:9]
	s_or_b64 s[68:69], s[68:69], s[70:71]
	s_waitcnt lgkmcnt(2)
	v_cmp_eq_f32_e64 s[70:71], v6, v19
	v_add3_u32 v2, v3, v2, v4
	v_cndmask_b32_e64 v3, 0, 1, s[68:69]
	v_cmp_gt_f32_e64 s[68:69], v6, v19
	s_and_b64 s[70:71], s[70:71], s[10:11]
	s_or_b64 s[68:69], s[68:69], s[70:71]
	v_cmp_eq_f32_e64 s[70:71], v7, v19
	v_cndmask_b32_e64 v4, 0, 1, s[68:69]
	v_cmp_gt_f32_e64 s[68:69], v7, v19
	s_and_b64 s[70:71], s[70:71], s[12:13]
	s_or_b64 s[68:69], s[68:69], s[70:71]
	v_cmp_eq_f32_e64 s[70:71], v8, v19
	v_add3_u32 v2, v2, v3, v4
	v_cndmask_b32_e64 v3, 0, 1, s[68:69]
	v_cmp_gt_f32_e64 s[68:69], v8, v19
	s_and_b64 s[70:71], s[70:71], s[14:15]
	s_or_b64 s[68:69], s[68:69], s[70:71]
	v_cmp_eq_f32_e64 s[70:71], v9, v19
	v_cndmask_b32_e64 v4, 0, 1, s[68:69]
	v_cmp_gt_f32_e64 s[68:69], v9, v19
	s_and_b64 s[70:71], s[70:71], s[16:17]
	s_or_b64 s[68:69], s[68:69], s[70:71]
	s_waitcnt lgkmcnt(1)
	v_cmp_eq_f32_e64 s[70:71], v10, v19
	v_add3_u32 v2, v2, v3, v4
	v_cndmask_b32_e64 v3, 0, 1, s[68:69]
	v_cmp_gt_f32_e64 s[68:69], v10, v19
	s_and_b64 s[70:71], s[70:71], s[18:19]
	s_or_b64 s[68:69], s[68:69], s[70:71]
	v_cmp_eq_f32_e64 s[70:71], v11, v19
	v_cndmask_b32_e64 v4, 0, 1, s[68:69]
	v_cmp_gt_f32_e64 s[68:69], v11, v19
	s_and_b64 s[70:71], s[70:71], s[20:21]
	s_or_b64 s[68:69], s[68:69], s[70:71]
	v_cmp_eq_f32_e64 s[70:71], v12, v19
	v_add3_u32 v2, v2, v3, v4
	v_cndmask_b32_e64 v3, 0, 1, s[68:69]
	v_cmp_gt_f32_e64 s[68:69], v12, v19
	s_and_b64 s[70:71], s[70:71], s[22:23]
	s_or_b64 s[68:69], s[68:69], s[70:71]
	v_cmp_eq_f32_e64 s[70:71], v13, v19
	v_cndmask_b32_e64 v4, 0, 1, s[68:69]
	v_cmp_gt_f32_e64 s[68:69], v13, v19
	s_and_b64 s[70:71], s[70:71], s[24:25]
	s_or_b64 s[68:69], s[68:69], s[70:71]
	s_waitcnt lgkmcnt(0)
	v_cmp_eq_f32_e64 s[70:71], v14, v19
	v_cndmask_b32_e64 v7, 0, 1, s[68:69]
	v_cmp_gt_f32_e64 s[68:69], v14, v19
	s_and_b64 s[70:71], s[70:71], s[28:29]
	s_or_b64 s[68:69], s[68:69], s[70:71]
	v_cmp_eq_f32_e64 s[70:71], v15, v19
	v_add3_u32 v6, v2, v3, v4
	ds_read_b128 v[2:5], v18 offset:2112
	v_cndmask_b32_e64 v8, 0, 1, s[68:69]
	v_cmp_gt_f32_e64 s[68:69], v15, v19
	s_and_b64 s[70:71], s[70:71], s[30:31]
	s_or_b64 s[68:69], s[68:69], s[70:71]
	v_cmp_eq_f32_e64 s[70:71], v16, v19
	v_add3_u32 v6, v6, v7, v8
	v_cndmask_b32_e64 v7, 0, 1, s[68:69]
	v_cmp_gt_f32_e64 s[68:69], v16, v19
	s_and_b64 s[70:71], s[70:71], s[34:35]
	s_or_b64 s[68:69], s[68:69], s[70:71]
	v_cmp_eq_f32_e64 s[70:71], v17, v19
	v_cndmask_b32_e64 v8, 0, 1, s[68:69]
	v_cmp_gt_f32_e64 s[68:69], v17, v19
	s_and_b64 s[70:71], s[70:71], s[36:37]
	s_or_b64 s[68:69], s[68:69], s[70:71]
	s_waitcnt lgkmcnt(0)
	v_cmp_eq_f32_e64 s[70:71], v2, v19
	v_add3_u32 v6, v6, v7, v8
	v_cndmask_b32_e64 v7, 0, 1, s[68:69]
	v_cmp_gt_f32_e64 s[68:69], v2, v19
	s_and_b64 s[70:71], s[70:71], s[38:39]
	s_or_b64 s[68:69], s[68:69], s[70:71]
	v_cmp_eq_f32_e64 s[70:71], v3, v19
	v_cndmask_b32_e64 v2, 0, 1, s[68:69]
	v_cmp_gt_f32_e64 s[68:69], v3, v19
	s_and_b64 s[70:71], s[70:71], s[40:41]
	s_or_b64 s[68:69], s[68:69], s[70:71]
	v_cmp_eq_f32_e64 s[70:71], v4, v19
	v_cndmask_b32_e64 v3, 0, 1, s[68:69]
	v_cmp_gt_f32_e64 s[68:69], v4, v19
	s_and_b64 s[70:71], s[70:71], s[42:43]
	s_or_b64 s[68:69], s[68:69], s[70:71]
	v_add3_u32 v2, v6, v7, v2
	v_cndmask_b32_e64 v4, 0, 1, s[68:69]
	v_add3_u32 v10, v2, v3, v4
	v_cmp_gt_f32_e64 s[68:69], v5, v19
	v_cmp_eq_f32_e64 s[70:71], v5, v19
	ds_read_b128 v[2:5], v18 offset:2128
	ds_read_b128 v[6:9], v18 offset:2144
	s_and_b64 s[70:71], s[70:71], s[26:27]
	s_or_b64 s[68:69], s[68:69], s[70:71]
	v_cndmask_b32_e64 v11, 0, 1, s[68:69]
	s_waitcnt lgkmcnt(1)
	v_cmp_eq_f32_e64 s[70:71], v2, v19
	v_cmp_gt_f32_e64 s[68:69], v2, v19
	s_and_b64 s[70:71], s[70:71], s[46:47]
	s_or_b64 s[68:69], s[68:69], s[70:71]
	v_cmp_eq_f32_e64 s[70:71], v3, v19
	v_cndmask_b32_e64 v2, 0, 1, s[68:69]
	v_cmp_gt_f32_e64 s[68:69], v3, v19
	s_and_b64 s[70:71], s[70:71], s[48:49]
	s_or_b64 s[68:69], s[68:69], s[70:71]
	v_cmp_eq_f32_e64 s[70:71], v4, v19
	v_cndmask_b32_e64 v3, 0, 1, s[68:69]
	v_cmp_gt_f32_e64 s[68:69], v4, v19
	s_and_b64 s[70:71], s[70:71], s[50:51]
	s_or_b64 s[68:69], s[68:69], s[70:71]
	v_cmp_eq_f32_e64 s[70:71], v5, v19
	v_cndmask_b32_e64 v4, 0, 1, s[68:69]
	v_cmp_gt_f32_e64 s[68:69], v5, v19
	s_and_b64 s[70:71], s[70:71], s[52:53]
	v_add3_u32 v2, v10, v11, v2
	s_or_b64 s[68:69], s[68:69], s[70:71]
	s_waitcnt lgkmcnt(0)
	v_cmp_eq_f32_e64 s[70:71], v6, v19
	v_add3_u32 v2, v2, v3, v4
	v_cndmask_b32_e64 v3, 0, 1, s[68:69]
	v_cmp_gt_f32_e64 s[68:69], v6, v19
	s_and_b64 s[70:71], s[70:71], s[54:55]
	s_or_b64 s[68:69], s[68:69], s[70:71]
	v_cmp_eq_f32_e64 s[70:71], v7, v19
	v_cndmask_b32_e64 v4, 0, 1, s[68:69]
	v_cmp_gt_f32_e64 s[68:69], v7, v19
	s_and_b64 s[70:71], s[70:71], s[56:57]
	s_or_b64 s[68:69], s[68:69], s[70:71]
	v_cmp_eq_f32_e64 s[70:71], v8, v19
	v_add3_u32 v2, v2, v3, v4
	v_cndmask_b32_e64 v3, 0, 1, s[68:69]
	v_cmp_gt_f32_e64 s[68:69], v8, v19
	s_and_b64 s[70:71], s[70:71], s[58:59]
	s_or_b64 s[68:69], s[68:69], s[70:71]
	v_cndmask_b32_e64 v4, 0, 1, s[68:69]
	v_add3_u32 v6, v2, v3, v4
	ds_read_b128 v[2:5], v18 offset:2160
	v_cmp_eq_f32_e64 s[70:71], v9, v19
	v_cmp_gt_f32_e64 s[68:69], v9, v19
	s_and_b64 s[70:71], s[70:71], s[44:45]
	s_or_b64 s[68:69], s[68:69], s[70:71]
	s_waitcnt lgkmcnt(0)
	v_cmp_eq_f32_e64 s[70:71], v2, v19
	v_cndmask_b32_e64 v7, 0, 1, s[68:69]
	v_cmp_gt_f32_e64 s[68:69], v2, v19
	s_and_b64 s[70:71], s[70:71], s[60:61]
	s_or_b64 s[68:69], s[68:69], s[70:71]
	v_cmp_eq_f32_e64 s[70:71], v3, v19
	v_cndmask_b32_e64 v2, 0, 1, s[68:69]
	v_cmp_gt_f32_e64 s[68:69], v3, v19
	s_and_b64 s[70:71], s[70:71], s[62:63]
	s_or_b64 s[68:69], s[68:69], s[70:71]
	v_cmp_eq_f32_e64 s[70:71], v4, v19
	v_cndmask_b32_e64 v3, 0, 1, s[68:69]
	v_cmp_gt_f32_e64 s[68:69], v4, v19
	s_and_b64 s[70:71], s[64:65], s[70:71]
	s_or_b64 s[68:69], s[68:69], s[70:71]
	v_add3_u32 v2, v6, v7, v2
	v_cndmask_b32_e64 v4, 0, 1, s[68:69]
	v_cmp_gt_f32_e64 s[68:69], v5, v19
	s_nop 1
	v_addc_co_u32_e64 v2, s[68:69], v2, v3, s[68:69]
	v_add_u32_e32 v2, v2, v4
	v_cmp_gt_u32_e64 s[70:71], 16, v2
	s_and_saveexec_b64 s[68:69], vcc
	v_mov_b32_e32 v2, s89
	v_mov_b64_e32 v[4:5], s[70:71]
	ds_write_b64 v2, v[4:5] offset:3088
	s_or_b64 exec, exec, s[68:69]
	v_lshl_add_u32 v16, v0, 2, s89
	ds_read_b32 v17, v1 offset:2048
	ds_read_b128 v[0:3], v16 offset:2048
	ds_read_b128 v[4:7], v16 offset:2064
	ds_read_b128 v[8:11], v16 offset:2080
	ds_read_b128 v[12:15], v16 offset:2096
	s_waitcnt lgkmcnt(3)
	v_cmp_eq_f32_e64 s[70:71], v0, v17
	v_cmp_gt_f32_e64 s[68:69], v0, v17
	s_and_b64 s[0:1], s[0:1], s[70:71]
	s_or_b64 s[0:1], s[68:69], s[0:1]
	v_cmp_eq_f32_e64 s[68:69], v1, v17
	v_cndmask_b32_e64 v0, 0, 1, s[0:1]
	v_cmp_gt_f32_e64 s[0:1], v1, v17
	s_and_b64 s[66:67], s[68:69], s[66:67]
	s_or_b64 s[0:1], s[0:1], s[66:67]
	v_cmp_eq_f32_e64 s[66:67], v2, v17
	v_cndmask_b32_e64 v1, 0, 1, s[0:1]
	v_cmp_gt_f32_e64 s[0:1], v2, v17
	s_and_b64 s[4:5], s[66:67], s[4:5]
	s_or_b64 s[0:1], s[0:1], s[4:5]
	v_cmp_eq_f32_e64 s[4:5], v3, v17
	v_cndmask_b32_e64 v2, 0, 1, s[0:1]
	v_cmp_gt_f32_e64 s[0:1], v3, v17
	s_and_b64 s[4:5], s[4:5], s[8:9]
	s_or_b64 s[0:1], s[0:1], s[4:5]
	s_waitcnt lgkmcnt(2)
	v_cmp_eq_f32_e64 s[4:5], v4, v17
	v_add3_u32 v0, v1, v0, v2
	v_cndmask_b32_e64 v1, 0, 1, s[0:1]
	v_cmp_gt_f32_e64 s[0:1], v4, v17
	s_and_b64 s[4:5], s[4:5], s[10:11]
	s_or_b64 s[0:1], s[0:1], s[4:5]
	v_cmp_eq_f32_e64 s[4:5], v5, v17
	v_cndmask_b32_e64 v2, 0, 1, s[0:1]
	v_cmp_gt_f32_e64 s[0:1], v5, v17
	s_and_b64 s[4:5], s[4:5], s[12:13]
	s_or_b64 s[0:1], s[0:1], s[4:5]
	v_cmp_eq_f32_e64 s[4:5], v6, v17
	v_add3_u32 v0, v0, v1, v2
	v_cndmask_b32_e64 v1, 0, 1, s[0:1]
	v_cmp_gt_f32_e64 s[0:1], v6, v17
	s_and_b64 s[4:5], s[4:5], s[14:15]
	s_or_b64 s[0:1], s[0:1], s[4:5]
	v_cmp_eq_f32_e64 s[4:5], v7, v17
	v_cndmask_b32_e64 v2, 0, 1, s[0:1]
	v_cmp_gt_f32_e64 s[0:1], v7, v17
	s_and_b64 s[4:5], s[4:5], s[16:17]
	s_or_b64 s[0:1], s[0:1], s[4:5]
	s_waitcnt lgkmcnt(1)
	v_cmp_eq_f32_e64 s[4:5], v8, v17
	v_add3_u32 v0, v0, v1, v2
	v_cndmask_b32_e64 v1, 0, 1, s[0:1]
	v_cmp_gt_f32_e64 s[0:1], v8, v17
	s_and_b64 s[4:5], s[4:5], s[18:19]
	s_or_b64 s[0:1], s[0:1], s[4:5]
	v_cmp_eq_f32_e64 s[4:5], v9, v17
	v_cndmask_b32_e64 v2, 0, 1, s[0:1]
	v_cmp_gt_f32_e64 s[0:1], v9, v17
	s_and_b64 s[4:5], s[4:5], s[20:21]
	s_or_b64 s[0:1], s[0:1], s[4:5]
	v_cmp_eq_f32_e64 s[4:5], v10, v17
	v_add3_u32 v0, v0, v1, v2
	v_cndmask_b32_e64 v1, 0, 1, s[0:1]
	v_cmp_gt_f32_e64 s[0:1], v10, v17
	s_and_b64 s[4:5], s[4:5], s[22:23]
	s_or_b64 s[0:1], s[0:1], s[4:5]
	v_cmp_eq_f32_e64 s[4:5], v11, v17
	v_cndmask_b32_e64 v2, 0, 1, s[0:1]
	v_cmp_gt_f32_e64 s[0:1], v11, v17
	s_and_b64 s[4:5], s[4:5], s[24:25]
	s_or_b64 s[0:1], s[0:1], s[4:5]
	s_waitcnt lgkmcnt(0)
	v_cmp_eq_f32_e64 s[4:5], v12, v17
	v_cndmask_b32_e64 v5, 0, 1, s[0:1]
	v_cmp_gt_f32_e64 s[0:1], v12, v17
	s_and_b64 s[4:5], s[4:5], s[28:29]
	s_or_b64 s[0:1], s[0:1], s[4:5]
	v_cmp_eq_f32_e64 s[4:5], v13, v17
	v_add3_u32 v4, v0, v1, v2
	ds_read_b128 v[0:3], v16 offset:2112
	v_cndmask_b32_e64 v6, 0, 1, s[0:1]
	v_cmp_gt_f32_e64 s[0:1], v13, v17
	s_and_b64 s[4:5], s[4:5], s[30:31]
	s_or_b64 s[0:1], s[0:1], s[4:5]
	v_cmp_eq_f32_e64 s[4:5], v14, v17
	v_add3_u32 v4, v4, v5, v6
	v_cndmask_b32_e64 v5, 0, 1, s[0:1]
	v_cmp_gt_f32_e64 s[0:1], v14, v17
	s_and_b64 s[4:5], s[4:5], s[34:35]
	s_or_b64 s[0:1], s[0:1], s[4:5]
	v_cmp_eq_f32_e64 s[4:5], v15, v17
	v_cndmask_b32_e64 v6, 0, 1, s[0:1]
	v_cmp_gt_f32_e64 s[0:1], v15, v17
	s_and_b64 s[4:5], s[4:5], s[36:37]
	s_or_b64 s[0:1], s[0:1], s[4:5]
	s_waitcnt lgkmcnt(0)
	v_cmp_eq_f32_e64 s[4:5], v0, v17
	v_add3_u32 v4, v4, v5, v6
	v_cndmask_b32_e64 v5, 0, 1, s[0:1]
	v_cmp_gt_f32_e64 s[0:1], v0, v17
	s_and_b64 s[4:5], s[4:5], s[38:39]
	s_or_b64 s[0:1], s[0:1], s[4:5]
	v_cmp_eq_f32_e64 s[4:5], v1, v17
	v_cndmask_b32_e64 v0, 0, 1, s[0:1]
	v_cmp_gt_f32_e64 s[0:1], v1, v17
	s_and_b64 s[4:5], s[4:5], s[40:41]
	s_or_b64 s[0:1], s[0:1], s[4:5]
	v_cmp_eq_f32_e64 s[4:5], v2, v17
	v_cndmask_b32_e64 v1, 0, 1, s[0:1]
	v_cmp_gt_f32_e64 s[0:1], v2, v17
	s_and_b64 s[4:5], s[4:5], s[42:43]
	s_or_b64 s[0:1], s[0:1], s[4:5]
	v_add3_u32 v0, v4, v5, v0
	v_cndmask_b32_e64 v2, 0, 1, s[0:1]
	v_add3_u32 v8, v0, v1, v2
	v_cmp_gt_f32_e64 s[0:1], v3, v17
	v_cmp_eq_f32_e64 s[4:5], v3, v17
	ds_read_b128 v[0:3], v16 offset:2128
	ds_read_b128 v[4:7], v16 offset:2144
	s_and_b64 s[4:5], s[4:5], s[26:27]
	s_or_b64 s[0:1], s[0:1], s[4:5]
	v_cndmask_b32_e64 v9, 0, 1, s[0:1]
	s_waitcnt lgkmcnt(1)
	v_cmp_eq_f32_e64 s[4:5], v0, v17
	v_cmp_gt_f32_e64 s[0:1], v0, v17
	s_and_b64 s[4:5], s[4:5], s[46:47]
	s_or_b64 s[0:1], s[0:1], s[4:5]
	v_cmp_eq_f32_e64 s[4:5], v1, v17
	v_cndmask_b32_e64 v0, 0, 1, s[0:1]
	v_cmp_gt_f32_e64 s[0:1], v1, v17
	s_and_b64 s[4:5], s[4:5], s[48:49]
	s_or_b64 s[0:1], s[0:1], s[4:5]
	v_cmp_eq_f32_e64 s[4:5], v2, v17
	v_cndmask_b32_e64 v1, 0, 1, s[0:1]
	v_cmp_gt_f32_e64 s[0:1], v2, v17
	s_and_b64 s[4:5], s[4:5], s[50:51]
	s_or_b64 s[0:1], s[0:1], s[4:5]
	v_cmp_eq_f32_e64 s[4:5], v3, v17
	v_cndmask_b32_e64 v2, 0, 1, s[0:1]
	v_cmp_gt_f32_e64 s[0:1], v3, v17
	s_and_b64 s[4:5], s[4:5], s[52:53]
	v_add3_u32 v0, v8, v9, v0
	s_or_b64 s[0:1], s[0:1], s[4:5]
	s_waitcnt lgkmcnt(0)
	v_cmp_eq_f32_e64 s[4:5], v4, v17
	v_add3_u32 v0, v0, v1, v2
	v_cndmask_b32_e64 v1, 0, 1, s[0:1]
	v_cmp_gt_f32_e64 s[0:1], v4, v17
	s_and_b64 s[4:5], s[4:5], s[54:55]
	s_or_b64 s[0:1], s[0:1], s[4:5]
	v_cmp_eq_f32_e64 s[4:5], v5, v17
	v_cndmask_b32_e64 v2, 0, 1, s[0:1]
	v_cmp_gt_f32_e64 s[0:1], v5, v17
	s_and_b64 s[4:5], s[4:5], s[56:57]
	s_or_b64 s[0:1], s[0:1], s[4:5]
	v_cmp_eq_f32_e64 s[4:5], v6, v17
	v_add3_u32 v0, v0, v1, v2
	v_cndmask_b32_e64 v1, 0, 1, s[0:1]
	v_cmp_gt_f32_e64 s[0:1], v6, v17
	s_and_b64 s[4:5], s[4:5], s[58:59]
	s_or_b64 s[0:1], s[0:1], s[4:5]
	v_cndmask_b32_e64 v2, 0, 1, s[0:1]
	v_add3_u32 v4, v0, v1, v2
	ds_read_b128 v[0:3], v16 offset:2160
	v_cmp_eq_f32_e64 s[4:5], v7, v17
	v_cmp_gt_f32_e64 s[0:1], v7, v17
	s_and_b64 s[4:5], s[4:5], s[44:45]
	s_or_b64 s[0:1], s[0:1], s[4:5]
	s_waitcnt lgkmcnt(0)
	v_cmp_eq_f32_e64 s[4:5], v0, v17
	v_cndmask_b32_e64 v5, 0, 1, s[0:1]
	v_cmp_gt_f32_e64 s[0:1], v0, v17
	s_and_b64 s[4:5], s[4:5], s[60:61]
	s_or_b64 s[0:1], s[0:1], s[4:5]
	v_cmp_eq_f32_e64 s[4:5], v1, v17
	v_cndmask_b32_e64 v0, 0, 1, s[0:1]
	v_cmp_gt_f32_e64 s[0:1], v1, v17
	s_and_b64 s[4:5], s[4:5], s[62:63]
	s_or_b64 s[0:1], s[0:1], s[4:5]
	v_cmp_eq_f32_e64 s[4:5], v2, v17
	v_cndmask_b32_e64 v1, 0, 1, s[0:1]
	v_cmp_gt_f32_e64 s[0:1], v2, v17
	s_and_b64 s[4:5], s[64:65], s[4:5]
	s_or_b64 s[0:1], s[0:1], s[4:5]
	v_add3_u32 v0, v4, v5, v0
	v_cndmask_b32_e64 v2, 0, 1, s[0:1]
	v_cmp_gt_f32_e64 s[0:1], v3, v17
	s_nop 1
	v_addc_co_u32_e64 v0, s[0:1], v0, v1, s[0:1]
	v_add_u32_e32 v0, v0, v2
	v_cmp_gt_u32_e64 s[4:5], 16, v0
	s_and_saveexec_b64 s[0:1], vcc
	v_mov_b32_e32 v0, s89
	v_mov_b64_e32 v[2:3], s[4:5]
	ds_write_b64 v0, v[2:3] offset:3096
	s_or_b64 exec, exec, s[0:1]
	s_waitcnt lgkmcnt(0)
	v_lshl_add_u32 v0, v132, 2, s89
	ds_read_b32 v106, v0 offset:3072
	s_waitcnt lgkmcnt(0)
	s_waitcnt lgkmcnt(0)
	v_and_b32_e32 v0, 1, v106
	v_cmp_ne_u32_e64 s[0:1], 0, v0
	v_bfe_u32 v0, v106, 1, 1
	v_cmp_ne_u32_e64 s[68:69], 0, v0
	v_bfe_u32 v0, v106, 2, 1
	v_cmp_ne_u32_e64 s[4:5], 0, v0
	v_bfe_u32 v0, v106, 3, 1
	v_cmp_ne_u32_e64 s[8:9], 0, v0
	v_bfe_u32 v0, v106, 4, 1
	v_cmp_ne_u32_e64 s[10:11], 0, v0
	v_bfe_u32 v0, v106, 5, 1
	v_cmp_ne_u32_e64 s[12:13], 0, v0
	v_bfe_u32 v0, v106, 6, 1
	v_cmp_ne_u32_e64 s[14:15], 0, v0
	v_bfe_u32 v0, v106, 7, 1
	v_cmp_ne_u32_e64 s[16:17], 0, v0
	v_bfe_u32 v0, v106, 8, 1
	v_cmp_ne_u32_e64 s[18:19], 0, v0
	v_bfe_u32 v0, v106, 9, 1
	v_cmp_ne_u32_e64 s[20:21], 0, v0
	v_bfe_u32 v0, v106, 10, 1
	v_cmp_ne_u32_e64 s[22:23], 0, v0
	v_bfe_u32 v0, v106, 11, 1
	v_cmp_ne_u32_e64 s[24:25], 0, v0
	v_bfe_u32 v0, v106, 12, 1
	v_cmp_ne_u32_e64 s[26:27], 0, v0
	v_bfe_u32 v0, v106, 13, 1
	v_cmp_ne_u32_e64 s[28:29], 0, v0
	v_bfe_u32 v0, v106, 14, 1
	v_cmp_ne_u32_e64 s[30:31], 0, v0
	v_bfe_u32 v0, v106, 15, 1
	v_cmp_ne_u32_e64 s[34:35], 0, v0
	v_bfe_u32 v0, v106, 16, 1
	v_cmp_ne_u32_e64 s[36:37], 0, v0
	v_bfe_u32 v0, v106, 17, 1
	v_cmp_ne_u32_e64 s[38:39], 0, v0
	v_bfe_u32 v0, v106, 18, 1
	v_cmp_ne_u32_e64 s[40:41], 0, v0
	v_bfe_u32 v0, v106, 19, 1
	v_cmp_ne_u32_e64 s[42:43], 0, v0
	v_bfe_u32 v0, v106, 20, 1
	v_cmp_ne_u32_e64 s[44:45], 0, v0
	v_bfe_u32 v0, v106, 21, 1
	v_cmp_ne_u32_e64 s[46:47], 0, v0
	v_bfe_u32 v0, v106, 22, 1
	v_cmp_ne_u32_e64 s[48:49], 0, v0
	v_bfe_u32 v0, v106, 23, 1
	v_cmp_ne_u32_e64 s[50:51], 0, v0
	v_bfe_u32 v0, v106, 24, 1
	v_cmp_ne_u32_e64 s[52:53], 0, v0
	v_bfe_u32 v0, v106, 25, 1
	v_cmp_ne_u32_e64 s[54:55], 0, v0
	v_bfe_u32 v0, v106, 26, 1
	v_cmp_ne_u32_e64 s[56:57], 0, v0
	v_bfe_u32 v0, v106, 27, 1
	v_cmp_ne_u32_e64 s[58:59], 0, v0
	v_bfe_u32 v0, v106, 28, 1
	v_cmp_ne_u32_e64 s[60:61], 0, v0
	v_bfe_u32 v0, v106, 29, 1
	v_cmp_ne_u32_e64 s[62:63], 0, v0
	v_bfe_u32 v0, v106, 30, 1
	v_cmp_ne_u32_e64 s[64:65], 0, v0
	v_cmp_gt_i32_e64 s[66:67], 0, v106
	s_and_saveexec_b64 s[70:71], vcc
	s_cbranch_execz .LBB0_1339
	s_cmp_eq_u64 s[66:67], 0
	s_cselect_b32 s66, 0, 0x80000000
	s_cmp_eq_u64 s[64:65], 0
	s_cselect_b32 s64, 0, 2.0
	s_cmp_eq_u64 s[62:63], 0
	s_cselect_b32 s62, 0, 0x20000000
	s_cmp_eq_u64 s[60:61], 0
	s_cselect_b32 s60, 0, 0x10000000
	s_cmp_eq_u64 s[58:59], 0
	s_cselect_b32 s58, 0, 0x8000000
	s_cmp_eq_u64 s[56:57], 0
	s_cselect_b32 s56, 0, 0x4000000
	s_cmp_eq_u64 s[54:55], 0
	s_cselect_b32 s54, 0, 0x2000000
	s_cmp_eq_u64 s[52:53], 0
	s_cselect_b32 s52, 0, 0x1000000
	s_cmp_eq_u64 s[50:51], 0
	s_cselect_b32 s50, 0, 0x800000
	s_cmp_eq_u64 s[48:49], 0
	s_cselect_b32 s48, 0, 0x400000
	s_cmp_eq_u64 s[46:47], 0
	s_cselect_b32 s46, 0, 0x200000
	s_cmp_eq_u64 s[44:45], 0
	s_cselect_b32 s44, 0, 0x100000
	s_cmp_eq_u64 s[42:43], 0
	s_cselect_b32 s42, 0, 0x80000
	s_cmp_eq_u64 s[40:41], 0
	s_cselect_b32 s40, 0, 0x40000
	s_cmp_eq_u64 s[38:39], 0
	s_cselect_b32 s38, 0, 0x20000
	s_cmp_eq_u64 s[36:37], 0
	s_cselect_b32 s36, 0, 0x10000
	s_cmp_eq_u64 s[34:35], 0
	s_cselect_b32 s34, 0, 0x8000
	s_cmp_eq_u64 s[30:31], 0
	s_cselect_b32 s30, 0, 0x4000
	s_cmp_eq_u64 s[28:29], 0
	s_cselect_b32 s28, 0, 0x2000
	s_cmp_eq_u64 s[26:27], 0
	s_cselect_b32 s26, 0, 0x1000
	s_cmp_eq_u64 s[24:25], 0
	s_cselect_b32 s24, 0, 0x800
	s_cmp_eq_u64 s[22:23], 0
	s_cselect_b32 s22, 0, 0x400
	s_cmp_eq_u64 s[20:21], 0
	s_cselect_b32 s20, 0, 0x200
	s_cmp_eq_u64 s[18:19], 0
	s_cselect_b32 s18, 0, 0x100
	s_cmp_eq_u64 s[16:17], 0
	s_cselect_b32 s16, 0, 0x80
	s_cmp_eq_u64 s[14:15], 0
	s_cselect_b32 s14, 0, 64
	s_cmp_eq_u64 s[12:13], 0
	s_cselect_b32 s12, 0, 32
	s_cmp_eq_u64 s[10:11], 0
	s_cselect_b32 s10, 0, 16
	s_cmp_eq_u64 s[8:9], 0
	s_cselect_b32 s8, 0, 8
	s_cmp_eq_u64 s[4:5], 0
	s_cselect_b32 s4, 0, 4
	s_cmp_eq_u64 s[68:69], 0
	s_cselect_b32 s5, 0, 2
	s_cmp_lg_u64 s[0:1], 0
	s_cselect_b64 s[0:1], -1, 0
	v_cndmask_b32_e64 v0, 0, 1, s[0:1]
	v_readlane_b32 s1, v253, 19
	v_readfirstlane_b32 s0, v0
	s_or_b32 s0, s5, s0
	s_or_b32 s0, s0, s4
	s_or_b32 s0, s0, s8
	s_or_b32 s0, s0, s10
	s_or_b32 s0, s0, s12
	s_or_b32 s0, s0, s14
	s_or_b32 s0, s0, s16
	s_or_b32 s0, s0, s18
	s_or_b32 s0, s0, s20
	s_or_b32 s0, s0, s22
	s_or_b32 s0, s0, s24
	s_or_b32 s0, s0, s26
	s_or_b32 s0, s0, s28
	s_or_b32 s0, s0, s30
	s_or_b32 s0, s0, s34
	s_or_b32 s0, s0, s36
	s_or_b32 s0, s0, s38
	s_or_b32 s0, s0, s40
	s_or_b32 s0, s0, s42
	s_or_b32 s0, s0, s44
	s_or_b32 s0, s0, s46
	s_or_b32 s0, s0, s48
	s_or_b32 s0, s0, s50
	s_or_b32 s0, s0, s52
	s_or_b32 s0, s0, s54
	s_or_b32 s0, s0, s56
	s_or_b32 s0, s0, s58
	s_or_b32 s0, s0, s60
	s_or_b32 s0, s0, s62
	s_or_b32 s0, s0, s64
	s_or_b32 s0, s0, s66
	v_mov_b32_e32 v0, s1
	v_mov_b32_e32 v1, s0
	ds_write_b32 v0, v1 offset:32704
